# grid barrier 4 replaced by per-XCD arrival counters (all producer stores for P4 written through with sc1, one atomic per workgroup, 8-word poll)
# baseline (speedup 1.0000x reference)
; __device__ __forceinline__ unsigned cvtpk(float lo, float hi) { f32x2 v = {lo, hi}; bf16x2_t b = __builtin_convertvector(v, bf16x2_t); return __builtin_bit_cast(unsigned, b); }
; __device__ __forceinline__ float silu_f(float v) { return v * __builtin_amdgcn_rcpf(1.0f + __builtin_amdgcn_exp2f(-v * LOG2E)); }
; __device__ __forceinline__ void conv_unit(unsigned char* ws, LAS unsigned char* lds, int t0) {
;     ...
;     const float* ln_g = KIN(I_LNG); const float* ln_b = KIN(I_LNB);
;     bf16_t* MIX = (bf16_t*)(ws + WS_MIX);
;     const f32x2 lg = *(const f32x2*)(ln_g + c0), lb = *(const f32x2*)(ln_b + c0);
; #pragma unroll
;     for (int t = 0; t < 32; ++t) {
;         const float mean = stat[t * 2], rstd = stat[t * 2 + 1];
;         const float v0 = (a0[t] - mean) * rstd * lg[0] + lb[0], v1 = (a1[t] - mean) * rstd * lg[1] + lb[1];
;         const unsigned gc = gcv[t];
;         *(unsigned*)(MIX + (size_t)(t0 + t) * DM + ATTW + c0) = cvtpk(silu_f(v0) * bf_lo(gc), silu_f(v1) * bf_hi(gc));
;     }
; __global__ void __launch_bounds__(512, 2) fwd_kernel(Args args) {
;     ...
;                 for (int cu = j; cu < SEQ / 32; cu += 120) conv_unit(ws, lds, 32 * cu);
.LBB0_439:
	s_or_b64 exec, exec, s[20:21]
	s_waitcnt lgkmcnt(0)
	s_barrier
	s_load_dwordx2 s[20:21], s[0:1], 0x88
	s_waitcnt lgkmcnt(0)
	s_load_dwordx2 s[28:29], s[0:1], 0x90
	s_waitcnt lgkmcnt(0)
	global_load_dwordx2 v[58:59], v14, s[20:21]
	global_load_dwordx2 v[66:67], v14, s[28:29]
	ds_read_b128 v[120:123], v15 offset:2048
	ds_read_b128 v[8:11], v15 offset:2064
	ds_read_b128 v[4:7], v15 offset:2080
	ds_read_b128 v[0:3], v15 offset:2096
	s_lshl_b64 s[20:21], s[36:37], 12
	s_waitcnt lgkmcnt(3)
	v_pk_add_f32 v[86:87], v[86:87], v[120:121] op_sel_hi:[1,0] neg_lo:[0,1] neg_hi:[0,1]
	s_waitcnt vmcnt(33)
	v_lshlrev_b32_e32 v124, 16, v119
	v_pk_mul_f32 v[86:87], v[120:121], v[86:87] op_sel:[1,0]
	v_and_b32_e32 v125, 0xffff0000, v119
	s_add_u32 s20, s34, s20
	s_addc_u32 s21, s35, s21
	v_pk_add_f32 v[84:85], v[84:85], v[122:123] op_sel_hi:[1,0] neg_lo:[0,1] neg_hi:[0,1]
	s_waitcnt lgkmcnt(2)
	v_pk_add_f32 v[82:83], v[82:83], v[8:9] op_sel_hi:[1,0] neg_lo:[0,1] neg_hi:[0,1]
	v_pk_add_f32 v[80:81], v[80:81], v[10:11] op_sel_hi:[1,0] neg_lo:[0,1] neg_hi:[0,1]
	v_pk_mul_f32 v[8:9], v[8:9], v[82:83] op_sel:[1,0]
	v_mov_b32_e32 v10, v11
	v_pk_mul_f32 v[10:11], v[10:11], v[80:81] op_sel_hi:[0,1]
	s_waitcnt vmcnt(0)
	v_pk_fma_f32 v[86:87], v[58:59], v[86:87], v[66:67]
	s_nop 0
	v_mul_f32_e32 v14, 0xbfb8aa3b, v86
	v_exp_f32_e32 v14, v14
	v_pk_fma_f32 v[8:9], v[58:59], v[8:9], v[66:67]
	v_pk_fma_f32 v[10:11], v[58:59], v[10:11], v[66:67]
	v_mul_f32_e32 v82, 0xbfb8aa3b, v8
	v_add_f32_e32 v14, 1.0, v14
	v_rcp_f32_e32 v120, v14
	v_mul_f32_e32 v14, 0xbfb8aa3b, v87
	v_exp_f32_e32 v14, v14
	v_mul_f32_e32 v83, 0xbfb8aa3b, v9
	v_exp_f32_e32 v82, v82
	v_exp_f32_e32 v83, v83
	v_add_f32_e32 v14, 1.0, v14
	v_rcp_f32_e32 v121, v14
	v_lshlrev_b32_e32 v14, 1, v12
	v_add_f32_e32 v82, 1.0, v82
	v_add_f32_e32 v83, 1.0, v83
	v_pk_mul_f32 v[86:87], v[86:87], v[120:121]
	v_mul_f32_e32 v80, 0xbfb8aa3b, v10
	v_pk_mul_f32 v[86:87], v[86:87], v[124:125]
	v_mul_f32_e32 v81, 0xbfb8aa3b, v11
	v_cvt_pk_bf16_f32 v119, v86, v87
	v_lshl_add_u64 v[86:87], s[20:21], 0, v[14:15]
	v_add_co_u32_e32 v86, vcc, s25, v86
	s_lshl_b64 s[20:21], s[30:31], 12
	s_nop 0
	v_addc_co_u32_e32 v87, vcc, 0, v87, vcc
	global_store_dword v[86:87], v119, off offset:2048 sc1
	v_lshlrev_b32_e32 v86, 16, v118
	v_and_b32_e32 v87, 0xffff0000, v118
	v_mov_b32_e32 v118, v123
	v_pk_mul_f32 v[84:85], v[118:119], v[84:85] op_sel_hi:[0,1]
	v_pk_fma_f32 v[84:85], v[58:59], v[84:85], v[66:67]
	s_add_u32 s20, s34, s20
	v_mul_f32_e32 v118, 0xbfb8aa3b, v84
	v_mul_f32_e32 v119, 0xbfb8aa3b, v85
	v_exp_f32_e32 v118, v118
	v_exp_f32_e32 v119, v119
	s_addc_u32 s21, s35, s21
	v_rcp_f32_e32 v82, v82
	v_add_f32_e32 v118, 1.0, v118
	v_add_f32_e32 v119, 1.0, v119
	v_rcp_f32_e32 v118, v118
	v_rcp_f32_e32 v119, v119
	v_rcp_f32_e32 v83, v83
	v_exp_f32_e32 v80, v80
	v_exp_f32_e32 v81, v81
	v_pk_mul_f32 v[84:85], v[84:85], v[118:119]
	v_pk_mul_f32 v[8:9], v[8:9], v[82:83]
	v_pk_mul_f32 v[84:85], v[84:85], v[86:87]
	v_add_f32_e32 v80, 1.0, v80
	v_cvt_pk_bf16_f32 v86, v84, v85
	v_lshl_add_u64 v[84:85], s[20:21], 0, v[14:15]
	v_add_co_u32_e32 v84, vcc, s25, v84
	s_lshl_b64 s[20:21], s[96:97], 12
	s_nop 0
	v_addc_co_u32_e32 v85, vcc, 0, v85, vcc
	global_store_dword v[84:85], v86, off offset:2048 sc1
	v_lshlrev_b32_e32 v84, 16, v117
	v_and_b32_e32 v85, 0xffff0000, v117
	s_add_u32 s20, s34, s20
	v_add_f32_e32 v81, 1.0, v81
	v_pk_mul_f32 v[8:9], v[8:9], v[84:85]
	s_addc_u32 s21, s35, s21
	v_rcp_f32_e32 v80, v80
	v_rcp_f32_e32 v81, v81
	v_cvt_pk_bf16_f32 v82, v8, v9
	v_lshl_add_u64 v[8:9], s[20:21], 0, v[14:15]
	v_add_co_u32_e32 v8, vcc, s25, v8
	s_lshl_b64 s[20:21], s[94:95], 12
	s_nop 0
	v_addc_co_u32_e32 v9, vcc, 0, v9, vcc
	global_store_dword v[8:9], v82, off offset:2048 sc1
	v_lshlrev_b32_e32 v8, 16, v116
	v_and_b32_e32 v9, 0xffff0000, v116
	v_pk_mul_f32 v[10:11], v[10:11], v[80:81]
	s_add_u32 s20, s34, s20
	v_pk_mul_f32 v[8:9], v[10:11], v[8:9]
	s_addc_u32 s21, s35, s21
	v_cvt_pk_bf16_f32 v10, v8, v9
	v_lshl_add_u64 v[8:9], s[20:21], 0, v[14:15]
	v_add_co_u32_e32 v8, vcc, s25, v8
	s_lshl_b64 s[20:21], s[92:93], 12
	s_nop 0
	v_addc_co_u32_e32 v9, vcc, 0, v9, vcc
	global_store_dword v[8:9], v10, off offset:2048 sc1
	s_waitcnt lgkmcnt(1)
	v_pk_add_f32 v[10:11], v[78:79], v[4:5] op_sel_hi:[1,0] neg_lo:[0,1] neg_hi:[0,1]
	v_lshlrev_b32_e32 v8, 16, v115
	v_pk_mul_f32 v[4:5], v[4:5], v[10:11] op_sel:[1,0]
	v_and_b32_e32 v9, 0xffff0000, v115
	v_pk_fma_f32 v[4:5], v[58:59], v[4:5], v[66:67]
	s_add_u32 s20, s34, s20
	v_mul_f32_e32 v10, 0xbfb8aa3b, v4
	v_mul_f32_e32 v11, 0xbfb8aa3b, v5
	v_exp_f32_e32 v10, v10
	v_exp_f32_e32 v11, v11
	s_addc_u32 s21, s35, s21
	v_add_f32_e32 v10, 1.0, v10
	v_add_f32_e32 v11, 1.0, v11
	v_rcp_f32_e32 v10, v10
	v_rcp_f32_e32 v11, v11
	s_nop 0
	v_pk_mul_f32 v[4:5], v[4:5], v[10:11]
	s_nop 0
	v_pk_mul_f32 v[4:5], v[4:5], v[8:9]
	s_nop 0
	v_cvt_pk_bf16_f32 v8, v4, v5
	v_lshl_add_u64 v[4:5], s[20:21], 0, v[14:15]
	v_add_co_u32_e32 v4, vcc, s25, v4
	s_lshl_b64 s[20:21], s[90:91], 12
	s_nop 0
	v_addc_co_u32_e32 v5, vcc, 0, v5, vcc
	global_store_dword v[4:5], v8, off offset:2048 sc1
	v_pk_add_f32 v[8:9], v[76:77], v[6:7] op_sel_hi:[1,0] neg_lo:[0,1] neg_hi:[0,1]
	v_mov_b32_e32 v6, v7
	v_pk_mul_f32 v[6:7], v[6:7], v[8:9] op_sel_hi:[0,1]
	v_pk_fma_f32 v[6:7], v[58:59], v[6:7], v[66:67]
	v_lshlrev_b32_e32 v4, 16, v114
	v_mul_f32_e32 v8, 0xbfb8aa3b, v6
	v_mul_f32_e32 v9, 0xbfb8aa3b, v7
	v_exp_f32_e32 v8, v8
	v_exp_f32_e32 v9, v9
	v_and_b32_e32 v5, 0xffff0000, v114
	s_add_u32 s20, s34, s20
	v_add_f32_e32 v8, 1.0, v8
	v_add_f32_e32 v9, 1.0, v9
	v_rcp_f32_e32 v8, v8
	v_rcp_f32_e32 v9, v9
	s_addc_u32 s21, s35, s21
	v_pk_mul_f32 v[6:7], v[6:7], v[8:9]
	s_nop 0
	v_pk_mul_f32 v[4:5], v[6:7], v[4:5]
	s_nop 0
	v_cvt_pk_bf16_f32 v6, v4, v5
	v_lshl_add_u64 v[4:5], s[20:21], 0, v[14:15]
	v_add_co_u32_e32 v4, vcc, s25, v4
	s_lshl_b64 s[20:21], s[88:89], 12
	s_nop 0
	v_addc_co_u32_e32 v5, vcc, 0, v5, vcc
	global_store_dword v[4:5], v6, off offset:2048 sc1
	s_waitcnt lgkmcnt(0)
; __device__ __forceinline__ unsigned cvtpk(float lo, float hi) { f32x2 v = {lo, hi}; bf16x2_t b = __builtin_convertvector(v, bf16x2_t); return __builtin_bit_cast(unsigned, b); }
; __device__ __forceinline__ float silu_f(float v) { return v * __builtin_amdgcn_rcpf(1.0f + __builtin_amdgcn_exp2f(-v * LOG2E)); }
; __device__ __forceinline__ void conv_unit(unsigned char* ws, LAS unsigned char* lds, int t0) {
;     ...
;     const f32x2 lg = *(const f32x2*)(ln_g + c0), lb = *(const f32x2*)(ln_b + c0);
; #pragma unroll
;     for (int t = 0; t < 32; ++t) {
;         const float mean = stat[t * 2], rstd = stat[t * 2 + 1];
;         const float v0 = (a0[t] - mean) * rstd * lg[0] + lb[0], v1 = (a1[t] - mean) * rstd * lg[1] + lb[1];
;         const unsigned gc = gcv[t];
;         *(unsigned*)(MIX + (size_t)(t0 + t) * DM + ATTW + c0) = cvtpk(silu_f(v0) * bf_lo(gc), silu_f(v1) * bf_hi(gc));
;     }
	v_pk_add_f32 v[6:7], v[74:75], v[0:1] op_sel_hi:[1,0] neg_lo:[0,1] neg_hi:[0,1]
	v_lshlrev_b32_e32 v4, 16, v113
	v_pk_mul_f32 v[0:1], v[0:1], v[6:7] op_sel:[1,0]
	v_and_b32_e32 v5, 0xffff0000, v113
	v_pk_fma_f32 v[0:1], v[58:59], v[0:1], v[66:67]
	s_add_u32 s20, s34, s20
	v_mul_f32_e32 v6, 0xbfb8aa3b, v0
	v_mul_f32_e32 v7, 0xbfb8aa3b, v1
	v_exp_f32_e32 v6, v6
	v_exp_f32_e32 v7, v7
	s_addc_u32 s21, s35, s21
	v_add_f32_e32 v6, 1.0, v6
	v_add_f32_e32 v7, 1.0, v7
	v_rcp_f32_e32 v6, v6
	v_rcp_f32_e32 v7, v7
	s_nop 0
	v_pk_mul_f32 v[0:1], v[0:1], v[6:7]
	s_nop 0
	v_pk_mul_f32 v[0:1], v[0:1], v[4:5]
	s_nop 0
	v_cvt_pk_bf16_f32 v4, v0, v1
	v_lshl_add_u64 v[0:1], s[20:21], 0, v[14:15]
	v_add_co_u32_e32 v0, vcc, s25, v0
	s_lshl_b64 s[20:21], s[86:87], 12
	s_nop 0
	v_addc_co_u32_e32 v1, vcc, 0, v1, vcc
	global_store_dword v[0:1], v4, off offset:2048 sc1
	v_pk_add_f32 v[4:5], v[72:73], v[2:3] op_sel_hi:[1,0] neg_lo:[0,1] neg_hi:[0,1]
	v_mov_b32_e32 v2, v3
	v_pk_mul_f32 v[2:3], v[2:3], v[4:5] op_sel_hi:[0,1]
	v_pk_fma_f32 v[2:3], v[58:59], v[2:3], v[66:67]
	v_lshlrev_b32_e32 v0, 16, v112
	v_mul_f32_e32 v4, 0xbfb8aa3b, v2
	v_mul_f32_e32 v5, 0xbfb8aa3b, v3
	v_exp_f32_e32 v4, v4
	v_exp_f32_e32 v5, v5
	v_and_b32_e32 v1, 0xffff0000, v112
	s_add_u32 s20, s34, s20
	v_add_f32_e32 v4, 1.0, v4
	v_add_f32_e32 v5, 1.0, v5
	v_rcp_f32_e32 v4, v4
	v_rcp_f32_e32 v5, v5
	s_addc_u32 s21, s35, s21
	v_pk_mul_f32 v[2:3], v[2:3], v[4:5]
	s_nop 0
	v_pk_mul_f32 v[0:1], v[2:3], v[0:1]
	v_lshlrev_b32_e32 v4, 16, v111
	v_cvt_pk_bf16_f32 v2, v0, v1
	v_lshl_add_u64 v[0:1], s[20:21], 0, v[14:15]
	v_add_co_u32_e32 v0, vcc, s25, v0
	s_lshl_b64 s[20:21], s[84:85], 12
	s_nop 0
	v_addc_co_u32_e32 v1, vcc, 0, v1, vcc
	global_store_dword v[0:1], v2, off offset:2048 sc1
	ds_read_b128 v[0:3], v15 offset:2112
	v_and_b32_e32 v5, 0xffff0000, v111
	s_add_u32 s20, s34, s20
	s_addc_u32 s21, s35, s21
	s_waitcnt lgkmcnt(0)
	v_pk_add_f32 v[6:7], v[70:71], v[0:1] op_sel_hi:[1,0] neg_lo:[0,1] neg_hi:[0,1]
	s_nop 0
	v_pk_mul_f32 v[0:1], v[0:1], v[6:7] op_sel:[1,0]
	s_nop 0
	v_pk_fma_f32 v[0:1], v[58:59], v[0:1], v[66:67]
	s_nop 0
	v_mul_f32_e32 v6, 0xbfb8aa3b, v0
	v_mul_f32_e32 v7, 0xbfb8aa3b, v1
	v_exp_f32_e32 v6, v6
	v_exp_f32_e32 v7, v7
	v_add_f32_e32 v6, 1.0, v6
	v_add_f32_e32 v7, 1.0, v7
	v_rcp_f32_e32 v6, v6
	v_rcp_f32_e32 v7, v7
	s_nop 0
	v_pk_mul_f32 v[0:1], v[0:1], v[6:7]
	s_nop 0
	v_pk_mul_f32 v[0:1], v[0:1], v[4:5]
	s_nop 0
	v_cvt_pk_bf16_f32 v4, v0, v1
	v_lshl_add_u64 v[0:1], s[20:21], 0, v[14:15]
	v_add_co_u32_e32 v0, vcc, s25, v0
	s_lshl_b64 s[20:21], s[82:83], 12
	s_nop 0
	v_addc_co_u32_e32 v1, vcc, 0, v1, vcc
	global_store_dword v[0:1], v4, off offset:2048 sc1
	v_pk_add_f32 v[4:5], v[68:69], v[2:3] op_sel_hi:[1,0] neg_lo:[0,1] neg_hi:[0,1]
	v_mov_b32_e32 v2, v3
	v_pk_mul_f32 v[2:3], v[2:3], v[4:5] op_sel_hi:[0,1]
	v_pk_fma_f32 v[2:3], v[58:59], v[2:3], v[66:67]
	v_lshlrev_b32_e32 v0, 16, v110
	v_mul_f32_e32 v4, 0xbfb8aa3b, v2
	v_mul_f32_e32 v5, 0xbfb8aa3b, v3
	v_exp_f32_e32 v4, v4
	v_exp_f32_e32 v5, v5
	v_and_b32_e32 v1, 0xffff0000, v110
	s_add_u32 s20, s34, s20
	v_add_f32_e32 v4, 1.0, v4
	v_add_f32_e32 v5, 1.0, v5
	v_rcp_f32_e32 v4, v4
	v_rcp_f32_e32 v5, v5
	s_addc_u32 s21, s35, s21
	v_pk_mul_f32 v[2:3], v[2:3], v[4:5]
	s_nop 0
	v_pk_mul_f32 v[0:1], v[2:3], v[0:1]
	v_lshlrev_b32_e32 v4, 16, v109
	v_cvt_pk_bf16_f32 v2, v0, v1
	v_lshl_add_u64 v[0:1], s[20:21], 0, v[14:15]
	v_add_co_u32_e32 v0, vcc, s25, v0
	s_lshl_b64 s[20:21], s[80:81], 12
	s_nop 0
	v_addc_co_u32_e32 v1, vcc, 0, v1, vcc
	global_store_dword v[0:1], v2, off offset:2048 sc1
	ds_read_b128 v[0:3], v15 offset:2128
	v_and_b32_e32 v5, 0xffff0000, v109
	s_add_u32 s20, s34, s20
	s_addc_u32 s21, s35, s21
	s_waitcnt lgkmcnt(0)
	v_pk_add_f32 v[6:7], v[64:65], v[0:1] op_sel_hi:[1,0] neg_lo:[0,1] neg_hi:[0,1]
	s_nop 0
	v_pk_mul_f32 v[0:1], v[0:1], v[6:7] op_sel:[1,0]
	s_nop 0
	v_pk_fma_f32 v[0:1], v[58:59], v[0:1], v[66:67]
	s_nop 0
	v_mul_f32_e32 v6, 0xbfb8aa3b, v0
	v_mul_f32_e32 v7, 0xbfb8aa3b, v1
	v_exp_f32_e32 v6, v6
	v_exp_f32_e32 v7, v7
	v_add_f32_e32 v6, 1.0, v6
	v_add_f32_e32 v7, 1.0, v7
	v_rcp_f32_e32 v6, v6
	v_rcp_f32_e32 v7, v7
	s_nop 0
	v_pk_mul_f32 v[0:1], v[0:1], v[6:7]
	s_nop 0
	v_pk_mul_f32 v[0:1], v[0:1], v[4:5]
	s_nop 0
	v_cvt_pk_bf16_f32 v4, v0, v1
	v_lshl_add_u64 v[0:1], s[20:21], 0, v[14:15]
	v_add_co_u32_e32 v0, vcc, s25, v0
	s_lshl_b64 s[20:21], s[78:79], 12
	s_nop 0
	v_addc_co_u32_e32 v1, vcc, 0, v1, vcc
	global_store_dword v[0:1], v4, off offset:2048 sc1
	v_pk_add_f32 v[4:5], v[62:63], v[2:3] op_sel_hi:[1,0] neg_lo:[0,1] neg_hi:[0,1]
	v_mov_b32_e32 v2, v3
	v_pk_mul_f32 v[2:3], v[2:3], v[4:5] op_sel_hi:[0,1]
	v_pk_fma_f32 v[2:3], v[58:59], v[2:3], v[66:67]
	v_lshlrev_b32_e32 v0, 16, v108
	v_mul_f32_e32 v4, 0xbfb8aa3b, v2
	v_mul_f32_e32 v5, 0xbfb8aa3b, v3
	v_exp_f32_e32 v4, v4
	v_exp_f32_e32 v5, v5
	v_and_b32_e32 v1, 0xffff0000, v108
	s_add_u32 s20, s34, s20
	v_add_f32_e32 v4, 1.0, v4
	v_add_f32_e32 v5, 1.0, v5
	v_rcp_f32_e32 v4, v4
	v_rcp_f32_e32 v5, v5
	s_addc_u32 s21, s35, s21
	v_pk_mul_f32 v[2:3], v[2:3], v[4:5]
	s_nop 0
	v_pk_mul_f32 v[0:1], v[2:3], v[0:1]
	v_lshlrev_b32_e32 v4, 16, v107
	v_cvt_pk_bf16_f32 v2, v0, v1
	v_lshl_add_u64 v[0:1], s[20:21], 0, v[14:15]
	v_add_co_u32_e32 v0, vcc, s25, v0
	s_lshl_b64 s[20:21], s[76:77], 12
	s_nop 0
	v_addc_co_u32_e32 v1, vcc, 0, v1, vcc
	global_store_dword v[0:1], v2, off offset:2048 sc1
	ds_read_b128 v[0:3], v15 offset:2144
	v_and_b32_e32 v5, 0xffff0000, v107
	s_add_u32 s20, s34, s20
	s_addc_u32 s21, s35, s21
	s_waitcnt lgkmcnt(0)
; __device__ __forceinline__ unsigned cvtpk(float lo, float hi) { f32x2 v = {lo, hi}; bf16x2_t b = __builtin_convertvector(v, bf16x2_t); return __builtin_bit_cast(unsigned, b); }
; __device__ __forceinline__ float silu_f(float v) { return v * __builtin_amdgcn_rcpf(1.0f + __builtin_amdgcn_exp2f(-v * LOG2E)); }
; __device__ __forceinline__ void conv_unit(unsigned char* ws, LAS unsigned char* lds, int t0) {
;     ...
;     const f32x2 lg = *(const f32x2*)(ln_g + c0), lb = *(const f32x2*)(ln_b + c0);
; #pragma unroll
;     for (int t = 0; t < 32; ++t) {
;         const float mean = stat[t * 2], rstd = stat[t * 2 + 1];
;         const float v0 = (a0[t] - mean) * rstd * lg[0] + lb[0], v1 = (a1[t] - mean) * rstd * lg[1] + lb[1];
;         const unsigned gc = gcv[t];
;         *(unsigned*)(MIX + (size_t)(t0 + t) * DM + ATTW + c0) = cvtpk(silu_f(v0) * bf_lo(gc), silu_f(v1) * bf_hi(gc));
;     }
	v_pk_add_f32 v[6:7], v[60:61], v[0:1] op_sel_hi:[1,0] neg_lo:[0,1] neg_hi:[0,1]
	s_nop 0
	v_pk_mul_f32 v[0:1], v[0:1], v[6:7] op_sel:[1,0]
	s_nop 0
	v_pk_fma_f32 v[0:1], v[58:59], v[0:1], v[66:67]
	s_nop 0
	v_mul_f32_e32 v6, 0xbfb8aa3b, v0
	v_mul_f32_e32 v7, 0xbfb8aa3b, v1
	v_exp_f32_e32 v6, v6
	v_exp_f32_e32 v7, v7
	v_add_f32_e32 v6, 1.0, v6
	v_add_f32_e32 v7, 1.0, v7
	v_rcp_f32_e32 v6, v6
	v_rcp_f32_e32 v7, v7
	s_nop 0
	v_pk_mul_f32 v[0:1], v[0:1], v[6:7]
	s_nop 0
	v_pk_mul_f32 v[0:1], v[0:1], v[4:5]
	s_nop 0
	v_cvt_pk_bf16_f32 v4, v0, v1
	v_lshl_add_u64 v[0:1], s[20:21], 0, v[14:15]
	v_add_co_u32_e32 v0, vcc, s25, v0
	s_lshl_b64 s[20:21], s[74:75], 12
	s_nop 0
	v_addc_co_u32_e32 v1, vcc, 0, v1, vcc
	global_store_dword v[0:1], v4, off offset:2048 sc1
	v_pk_add_f32 v[4:5], v[56:57], v[2:3] op_sel_hi:[1,0] neg_lo:[0,1] neg_hi:[0,1]
	v_mov_b32_e32 v2, v3
	v_pk_mul_f32 v[2:3], v[2:3], v[4:5] op_sel_hi:[0,1]
	v_pk_fma_f32 v[2:3], v[58:59], v[2:3], v[66:67]
	v_lshlrev_b32_e32 v0, 16, v106
	v_mul_f32_e32 v4, 0xbfb8aa3b, v2
	v_mul_f32_e32 v5, 0xbfb8aa3b, v3
	v_exp_f32_e32 v4, v4
	v_exp_f32_e32 v5, v5
	v_and_b32_e32 v1, 0xffff0000, v106
	s_add_u32 s20, s34, s20
	v_add_f32_e32 v4, 1.0, v4
	v_add_f32_e32 v5, 1.0, v5
	v_rcp_f32_e32 v4, v4
	v_rcp_f32_e32 v5, v5
	s_addc_u32 s21, s35, s21
	v_pk_mul_f32 v[2:3], v[2:3], v[4:5]
	s_nop 0
	v_pk_mul_f32 v[0:1], v[2:3], v[0:1]
	v_lshlrev_b32_e32 v4, 16, v105
	v_cvt_pk_bf16_f32 v2, v0, v1
	v_lshl_add_u64 v[0:1], s[20:21], 0, v[14:15]
	v_add_co_u32_e32 v0, vcc, s25, v0
	s_lshl_b64 s[20:21], s[72:73], 12
	s_nop 0
	v_addc_co_u32_e32 v1, vcc, 0, v1, vcc
	global_store_dword v[0:1], v2, off offset:2048 sc1
	ds_read_b128 v[0:3], v15 offset:2160
	v_and_b32_e32 v5, 0xffff0000, v105
	s_add_u32 s20, s34, s20
	s_addc_u32 s21, s35, s21
	s_waitcnt lgkmcnt(0)
	v_pk_add_f32 v[6:7], v[54:55], v[0:1] op_sel_hi:[1,0] neg_lo:[0,1] neg_hi:[0,1]
	s_nop 0
	v_pk_mul_f32 v[0:1], v[0:1], v[6:7] op_sel:[1,0]
	s_nop 0
	v_pk_fma_f32 v[0:1], v[58:59], v[0:1], v[66:67]
	s_nop 0
	v_mul_f32_e32 v6, 0xbfb8aa3b, v0
	v_mul_f32_e32 v7, 0xbfb8aa3b, v1
	v_exp_f32_e32 v6, v6
	v_exp_f32_e32 v7, v7
	v_add_f32_e32 v6, 1.0, v6
	v_add_f32_e32 v7, 1.0, v7
	v_rcp_f32_e32 v6, v6
	v_rcp_f32_e32 v7, v7
	s_nop 0
	v_pk_mul_f32 v[0:1], v[0:1], v[6:7]
	s_nop 0
	v_pk_mul_f32 v[0:1], v[0:1], v[4:5]
	s_nop 0
	v_cvt_pk_bf16_f32 v4, v0, v1
	v_lshl_add_u64 v[0:1], s[20:21], 0, v[14:15]
	v_add_co_u32_e32 v0, vcc, s25, v0
	s_lshl_b64 s[20:21], s[70:71], 12
	s_nop 0
	v_addc_co_u32_e32 v1, vcc, 0, v1, vcc
	global_store_dword v[0:1], v4, off offset:2048 sc1
	v_pk_add_f32 v[4:5], v[52:53], v[2:3] op_sel_hi:[1,0] neg_lo:[0,1] neg_hi:[0,1]
	v_mov_b32_e32 v2, v3
	v_pk_mul_f32 v[2:3], v[2:3], v[4:5] op_sel_hi:[0,1]
	v_pk_fma_f32 v[2:3], v[58:59], v[2:3], v[66:67]
	v_lshlrev_b32_e32 v0, 16, v104
	v_mul_f32_e32 v4, 0xbfb8aa3b, v2
	v_mul_f32_e32 v5, 0xbfb8aa3b, v3
	v_exp_f32_e32 v4, v4
	v_exp_f32_e32 v5, v5
	v_and_b32_e32 v1, 0xffff0000, v104
	s_add_u32 s20, s34, s20
	v_add_f32_e32 v4, 1.0, v4
	v_add_f32_e32 v5, 1.0, v5
	v_rcp_f32_e32 v4, v4
	v_rcp_f32_e32 v5, v5
	s_addc_u32 s21, s35, s21
	v_pk_mul_f32 v[2:3], v[2:3], v[4:5]
	s_nop 0
	v_pk_mul_f32 v[0:1], v[2:3], v[0:1]
	v_lshlrev_b32_e32 v4, 16, v103
	v_cvt_pk_bf16_f32 v2, v0, v1
	v_lshl_add_u64 v[0:1], s[20:21], 0, v[14:15]
	v_add_co_u32_e32 v0, vcc, s25, v0
	s_lshl_b64 s[20:21], s[68:69], 12
	s_nop 0
	v_addc_co_u32_e32 v1, vcc, 0, v1, vcc
	global_store_dword v[0:1], v2, off offset:2048 sc1
	ds_read_b128 v[0:3], v15 offset:2176
	v_and_b32_e32 v5, 0xffff0000, v103
	s_add_u32 s20, s34, s20
	s_addc_u32 s21, s35, s21
	s_waitcnt lgkmcnt(0)
	v_pk_add_f32 v[6:7], v[50:51], v[0:1] op_sel_hi:[1,0] neg_lo:[0,1] neg_hi:[0,1]
	s_nop 0
	v_pk_mul_f32 v[0:1], v[0:1], v[6:7] op_sel:[1,0]
	s_nop 0
	v_pk_fma_f32 v[0:1], v[58:59], v[0:1], v[66:67]
	s_nop 0
	v_mul_f32_e32 v6, 0xbfb8aa3b, v0
	v_mul_f32_e32 v7, 0xbfb8aa3b, v1
	v_exp_f32_e32 v6, v6
	v_exp_f32_e32 v7, v7
	v_add_f32_e32 v6, 1.0, v6
	v_add_f32_e32 v7, 1.0, v7
	v_rcp_f32_e32 v6, v6
	v_rcp_f32_e32 v7, v7
	s_nop 0
	v_pk_mul_f32 v[0:1], v[0:1], v[6:7]
	s_nop 0
	v_pk_mul_f32 v[0:1], v[0:1], v[4:5]
	s_nop 0
	v_cvt_pk_bf16_f32 v4, v0, v1
	v_lshl_add_u64 v[0:1], s[20:21], 0, v[14:15]
	v_add_co_u32_e32 v0, vcc, s25, v0
	s_lshl_b64 s[20:21], s[66:67], 12
	s_nop 0
	v_addc_co_u32_e32 v1, vcc, 0, v1, vcc
	global_store_dword v[0:1], v4, off offset:2048 sc1
	v_pk_add_f32 v[4:5], v[48:49], v[2:3] op_sel_hi:[1,0] neg_lo:[0,1] neg_hi:[0,1]
	v_mov_b32_e32 v2, v3
	v_pk_mul_f32 v[2:3], v[2:3], v[4:5] op_sel_hi:[0,1]
	v_pk_fma_f32 v[2:3], v[58:59], v[2:3], v[66:67]
	v_lshlrev_b32_e32 v0, 16, v102
	v_mul_f32_e32 v4, 0xbfb8aa3b, v2
	v_mul_f32_e32 v5, 0xbfb8aa3b, v3
	v_exp_f32_e32 v4, v4
	v_exp_f32_e32 v5, v5
	v_and_b32_e32 v1, 0xffff0000, v102
	s_add_u32 s20, s34, s20
	v_add_f32_e32 v4, 1.0, v4
	v_add_f32_e32 v5, 1.0, v5
	v_rcp_f32_e32 v4, v4
	v_rcp_f32_e32 v5, v5
	s_addc_u32 s21, s35, s21
	v_pk_mul_f32 v[2:3], v[2:3], v[4:5]
	s_nop 0
	v_pk_mul_f32 v[0:1], v[2:3], v[0:1]
	v_lshlrev_b32_e32 v4, 16, v101
	v_cvt_pk_bf16_f32 v2, v0, v1
	v_lshl_add_u64 v[0:1], s[20:21], 0, v[14:15]
	v_add_co_u32_e32 v0, vcc, s25, v0
	s_lshl_b64 s[20:21], s[64:65], 12
	s_nop 0
	v_addc_co_u32_e32 v1, vcc, 0, v1, vcc
	global_store_dword v[0:1], v2, off offset:2048 sc1
	ds_read_b128 v[0:3], v15 offset:2192
	v_and_b32_e32 v5, 0xffff0000, v101
	s_add_u32 s20, s34, s20
	s_addc_u32 s21, s35, s21
	s_waitcnt lgkmcnt(0)
; __device__ __forceinline__ unsigned cvtpk(float lo, float hi) { f32x2 v = {lo, hi}; bf16x2_t b = __builtin_convertvector(v, bf16x2_t); return __builtin_bit_cast(unsigned, b); }
; __device__ __forceinline__ float silu_f(float v) { return v * __builtin_amdgcn_rcpf(1.0f + __builtin_amdgcn_exp2f(-v * LOG2E)); }
; __device__ __forceinline__ void conv_unit(unsigned char* ws, LAS unsigned char* lds, int t0) {
;     ...
;     const f32x2 lg = *(const f32x2*)(ln_g + c0), lb = *(const f32x2*)(ln_b + c0);
; #pragma unroll
;     for (int t = 0; t < 32; ++t) {
;         const float mean = stat[t * 2], rstd = stat[t * 2 + 1];
;         const float v0 = (a0[t] - mean) * rstd * lg[0] + lb[0], v1 = (a1[t] - mean) * rstd * lg[1] + lb[1];
;         const unsigned gc = gcv[t];
;         *(unsigned*)(MIX + (size_t)(t0 + t) * DM + ATTW + c0) = cvtpk(silu_f(v0) * bf_lo(gc), silu_f(v1) * bf_hi(gc));
;     }
	v_pk_add_f32 v[6:7], v[46:47], v[0:1] op_sel_hi:[1,0] neg_lo:[0,1] neg_hi:[0,1]
	s_nop 0
	v_pk_mul_f32 v[0:1], v[0:1], v[6:7] op_sel:[1,0]
	s_nop 0
	v_pk_fma_f32 v[0:1], v[58:59], v[0:1], v[66:67]
	s_nop 0
	v_mul_f32_e32 v6, 0xbfb8aa3b, v0
	v_mul_f32_e32 v7, 0xbfb8aa3b, v1
	v_exp_f32_e32 v6, v6
	v_exp_f32_e32 v7, v7
	v_add_f32_e32 v6, 1.0, v6
	v_add_f32_e32 v7, 1.0, v7
	v_rcp_f32_e32 v6, v6
	v_rcp_f32_e32 v7, v7
	s_nop 0
	v_pk_mul_f32 v[0:1], v[0:1], v[6:7]
	s_nop 0
	v_pk_mul_f32 v[0:1], v[0:1], v[4:5]
	s_nop 0
	v_cvt_pk_bf16_f32 v4, v0, v1
	v_lshl_add_u64 v[0:1], s[20:21], 0, v[14:15]
	v_add_co_u32_e32 v0, vcc, s25, v0
	s_lshl_b64 s[20:21], s[62:63], 12
	s_nop 0
	v_addc_co_u32_e32 v1, vcc, 0, v1, vcc
	global_store_dword v[0:1], v4, off offset:2048 sc1
	v_pk_add_f32 v[4:5], v[44:45], v[2:3] op_sel_hi:[1,0] neg_lo:[0,1] neg_hi:[0,1]
	v_mov_b32_e32 v2, v3
	v_pk_mul_f32 v[2:3], v[2:3], v[4:5] op_sel_hi:[0,1]
	v_pk_fma_f32 v[2:3], v[58:59], v[2:3], v[66:67]
	v_lshlrev_b32_e32 v0, 16, v100
	v_mul_f32_e32 v4, 0xbfb8aa3b, v2
	v_mul_f32_e32 v5, 0xbfb8aa3b, v3
	v_exp_f32_e32 v4, v4
	v_exp_f32_e32 v5, v5
	v_and_b32_e32 v1, 0xffff0000, v100
	s_add_u32 s20, s34, s20
	v_add_f32_e32 v4, 1.0, v4
	v_add_f32_e32 v5, 1.0, v5
	v_rcp_f32_e32 v4, v4
	v_rcp_f32_e32 v5, v5
	s_addc_u32 s21, s35, s21
	v_pk_mul_f32 v[2:3], v[2:3], v[4:5]
	s_nop 0
	v_pk_mul_f32 v[0:1], v[2:3], v[0:1]
	v_lshlrev_b32_e32 v4, 16, v99
	v_cvt_pk_bf16_f32 v2, v0, v1
	v_lshl_add_u64 v[0:1], s[20:21], 0, v[14:15]
	v_add_co_u32_e32 v0, vcc, s25, v0
	s_lshl_b64 s[20:21], s[60:61], 12
	s_nop 0
	v_addc_co_u32_e32 v1, vcc, 0, v1, vcc
	global_store_dword v[0:1], v2, off offset:2048 sc1
	ds_read_b128 v[0:3], v15 offset:2208
	v_and_b32_e32 v5, 0xffff0000, v99
	s_add_u32 s20, s34, s20
	s_addc_u32 s21, s35, s21
	s_waitcnt lgkmcnt(0)
	v_pk_add_f32 v[6:7], v[42:43], v[0:1] op_sel_hi:[1,0] neg_lo:[0,1] neg_hi:[0,1]
	s_nop 0
	v_pk_mul_f32 v[0:1], v[0:1], v[6:7] op_sel:[1,0]
	s_nop 0
	v_pk_fma_f32 v[0:1], v[58:59], v[0:1], v[66:67]
	s_nop 0
	v_mul_f32_e32 v6, 0xbfb8aa3b, v0
	v_mul_f32_e32 v7, 0xbfb8aa3b, v1
	v_exp_f32_e32 v6, v6
	v_exp_f32_e32 v7, v7
	v_add_f32_e32 v6, 1.0, v6
	v_add_f32_e32 v7, 1.0, v7
	v_rcp_f32_e32 v6, v6
	v_rcp_f32_e32 v7, v7
	s_nop 0
	v_pk_mul_f32 v[0:1], v[0:1], v[6:7]
	s_nop 0
	v_pk_mul_f32 v[0:1], v[0:1], v[4:5]
	s_nop 0
	v_cvt_pk_bf16_f32 v4, v0, v1
	v_lshl_add_u64 v[0:1], s[20:21], 0, v[14:15]
	v_add_co_u32_e32 v0, vcc, s25, v0
	s_lshl_b64 s[20:21], s[58:59], 12
	s_nop 0
	v_addc_co_u32_e32 v1, vcc, 0, v1, vcc
	global_store_dword v[0:1], v4, off offset:2048 sc1
	v_pk_add_f32 v[4:5], v[40:41], v[2:3] op_sel_hi:[1,0] neg_lo:[0,1] neg_hi:[0,1]
	v_mov_b32_e32 v2, v3
	v_pk_mul_f32 v[2:3], v[2:3], v[4:5] op_sel_hi:[0,1]
	v_pk_fma_f32 v[2:3], v[58:59], v[2:3], v[66:67]
	v_lshlrev_b32_e32 v0, 16, v98
	v_mul_f32_e32 v4, 0xbfb8aa3b, v2
	v_mul_f32_e32 v5, 0xbfb8aa3b, v3
	v_exp_f32_e32 v4, v4
	v_exp_f32_e32 v5, v5
	v_and_b32_e32 v1, 0xffff0000, v98
	s_add_u32 s20, s34, s20
	v_add_f32_e32 v4, 1.0, v4
	v_add_f32_e32 v5, 1.0, v5
	v_rcp_f32_e32 v4, v4
	v_rcp_f32_e32 v5, v5
	s_addc_u32 s21, s35, s21
	v_pk_mul_f32 v[2:3], v[2:3], v[4:5]
	s_nop 0
	v_pk_mul_f32 v[0:1], v[2:3], v[0:1]
	v_lshlrev_b32_e32 v4, 16, v97
	v_cvt_pk_bf16_f32 v2, v0, v1
	v_lshl_add_u64 v[0:1], s[20:21], 0, v[14:15]
	v_add_co_u32_e32 v0, vcc, s25, v0
	s_lshl_b64 s[20:21], s[56:57], 12
	s_nop 0
	v_addc_co_u32_e32 v1, vcc, 0, v1, vcc
	global_store_dword v[0:1], v2, off offset:2048 sc1
	ds_read_b128 v[0:3], v15 offset:2224
	v_and_b32_e32 v5, 0xffff0000, v97
	s_add_u32 s20, s34, s20
	s_addc_u32 s21, s35, s21
	s_waitcnt lgkmcnt(0)
	v_pk_add_f32 v[6:7], v[38:39], v[0:1] op_sel_hi:[1,0] neg_lo:[0,1] neg_hi:[0,1]
	s_nop 0
	v_pk_mul_f32 v[0:1], v[0:1], v[6:7] op_sel:[1,0]
	s_nop 0
	v_pk_fma_f32 v[0:1], v[58:59], v[0:1], v[66:67]
	s_nop 0
	v_mul_f32_e32 v6, 0xbfb8aa3b, v0
	v_mul_f32_e32 v7, 0xbfb8aa3b, v1
	v_exp_f32_e32 v6, v6
	v_exp_f32_e32 v7, v7
	v_add_f32_e32 v6, 1.0, v6
	v_add_f32_e32 v7, 1.0, v7
	v_rcp_f32_e32 v6, v6
	v_rcp_f32_e32 v7, v7
	s_nop 0
	v_pk_mul_f32 v[0:1], v[0:1], v[6:7]
	s_nop 0
	v_pk_mul_f32 v[0:1], v[0:1], v[4:5]
	s_nop 0
	v_cvt_pk_bf16_f32 v4, v0, v1
	v_lshl_add_u64 v[0:1], s[20:21], 0, v[14:15]
	v_add_co_u32_e32 v0, vcc, s25, v0
	s_lshl_b64 s[20:21], s[54:55], 12
	s_nop 0
	v_addc_co_u32_e32 v1, vcc, 0, v1, vcc
	global_store_dword v[0:1], v4, off offset:2048 sc1
	v_pk_add_f32 v[4:5], v[36:37], v[2:3] op_sel_hi:[1,0] neg_lo:[0,1] neg_hi:[0,1]
	v_mov_b32_e32 v2, v3
	v_pk_mul_f32 v[2:3], v[2:3], v[4:5] op_sel_hi:[0,1]
	v_pk_fma_f32 v[2:3], v[58:59], v[2:3], v[66:67]
	v_lshlrev_b32_e32 v0, 16, v96
	v_mul_f32_e32 v4, 0xbfb8aa3b, v2
	v_mul_f32_e32 v5, 0xbfb8aa3b, v3
	v_exp_f32_e32 v4, v4
	v_exp_f32_e32 v5, v5
	v_and_b32_e32 v1, 0xffff0000, v96
	s_add_u32 s20, s34, s20
	v_add_f32_e32 v4, 1.0, v4
	v_add_f32_e32 v5, 1.0, v5
	v_rcp_f32_e32 v4, v4
	v_rcp_f32_e32 v5, v5
	s_addc_u32 s21, s35, s21
	v_pk_mul_f32 v[2:3], v[2:3], v[4:5]
	s_nop 0
	v_pk_mul_f32 v[0:1], v[2:3], v[0:1]
	v_lshlrev_b32_e32 v4, 16, v95
	v_cvt_pk_bf16_f32 v2, v0, v1
	v_lshl_add_u64 v[0:1], s[20:21], 0, v[14:15]
	v_add_co_u32_e32 v0, vcc, s25, v0
	s_lshl_b64 s[20:21], s[52:53], 12
	s_nop 0
	v_addc_co_u32_e32 v1, vcc, 0, v1, vcc
	global_store_dword v[0:1], v2, off offset:2048 sc1
	ds_read_b128 v[0:3], v15 offset:2240
	v_and_b32_e32 v5, 0xffff0000, v95
	s_add_u32 s20, s34, s20
	s_addc_u32 s21, s35, s21
	s_waitcnt lgkmcnt(0)
; __device__ __forceinline__ unsigned cvtpk(float lo, float hi) { f32x2 v = {lo, hi}; bf16x2_t b = __builtin_convertvector(v, bf16x2_t); return __builtin_bit_cast(unsigned, b); }
; __device__ __forceinline__ float silu_f(float v) { return v * __builtin_amdgcn_rcpf(1.0f + __builtin_amdgcn_exp2f(-v * LOG2E)); }
; __device__ __forceinline__ void conv_unit(unsigned char* ws, LAS unsigned char* lds, int t0) {
;     ...
;     const f32x2 lg = *(const f32x2*)(ln_g + c0), lb = *(const f32x2*)(ln_b + c0);
; #pragma unroll
;     for (int t = 0; t < 32; ++t) {
;         const float mean = stat[t * 2], rstd = stat[t * 2 + 1];
;         const float v0 = (a0[t] - mean) * rstd * lg[0] + lb[0], v1 = (a1[t] - mean) * rstd * lg[1] + lb[1];
;         const unsigned gc = gcv[t];
;         *(unsigned*)(MIX + (size_t)(t0 + t) * DM + ATTW + c0) = cvtpk(silu_f(v0) * bf_lo(gc), silu_f(v1) * bf_hi(gc));
;     }
	v_pk_add_f32 v[6:7], v[34:35], v[0:1] op_sel_hi:[1,0] neg_lo:[0,1] neg_hi:[0,1]
	s_nop 0
	v_pk_mul_f32 v[0:1], v[0:1], v[6:7] op_sel:[1,0]
	s_nop 0
	v_pk_fma_f32 v[0:1], v[58:59], v[0:1], v[66:67]
	s_nop 0
	v_mul_f32_e32 v6, 0xbfb8aa3b, v0
	v_mul_f32_e32 v7, 0xbfb8aa3b, v1
	v_exp_f32_e32 v6, v6
	v_exp_f32_e32 v7, v7
	v_add_f32_e32 v6, 1.0, v6
	v_add_f32_e32 v7, 1.0, v7
	v_rcp_f32_e32 v6, v6
	v_rcp_f32_e32 v7, v7
	s_nop 0
	v_pk_mul_f32 v[0:1], v[0:1], v[6:7]
	s_nop 0
	v_pk_mul_f32 v[0:1], v[0:1], v[4:5]
	s_nop 0
	v_cvt_pk_bf16_f32 v4, v0, v1
	v_lshl_add_u64 v[0:1], s[20:21], 0, v[14:15]
	v_add_co_u32_e32 v0, vcc, s25, v0
	s_lshl_b64 s[20:21], s[50:51], 12
	s_nop 0
	v_addc_co_u32_e32 v1, vcc, 0, v1, vcc
	global_store_dword v[0:1], v4, off offset:2048 sc1
	v_pk_add_f32 v[4:5], v[32:33], v[2:3] op_sel_hi:[1,0] neg_lo:[0,1] neg_hi:[0,1]
	v_mov_b32_e32 v2, v3
	v_pk_mul_f32 v[2:3], v[2:3], v[4:5] op_sel_hi:[0,1]
	v_pk_fma_f32 v[2:3], v[58:59], v[2:3], v[66:67]
	v_lshlrev_b32_e32 v0, 16, v94
	v_mul_f32_e32 v4, 0xbfb8aa3b, v2
	v_mul_f32_e32 v5, 0xbfb8aa3b, v3
	v_exp_f32_e32 v4, v4
	v_exp_f32_e32 v5, v5
	v_and_b32_e32 v1, 0xffff0000, v94
	s_add_u32 s20, s34, s20
	v_add_f32_e32 v4, 1.0, v4
	v_add_f32_e32 v5, 1.0, v5
	v_rcp_f32_e32 v4, v4
	v_rcp_f32_e32 v5, v5
	s_addc_u32 s21, s35, s21
	v_pk_mul_f32 v[2:3], v[2:3], v[4:5]
	s_nop 0
	v_pk_mul_f32 v[0:1], v[2:3], v[0:1]
	v_lshlrev_b32_e32 v4, 16, v93
	v_cvt_pk_bf16_f32 v2, v0, v1
	v_lshl_add_u64 v[0:1], s[20:21], 0, v[14:15]
	v_add_co_u32_e32 v0, vcc, s25, v0
	s_lshl_b64 s[20:21], s[48:49], 12
	s_nop 0
	v_addc_co_u32_e32 v1, vcc, 0, v1, vcc
	global_store_dword v[0:1], v2, off offset:2048 sc1
	ds_read_b128 v[0:3], v15 offset:2256
	v_and_b32_e32 v5, 0xffff0000, v93
	s_add_u32 s20, s34, s20
	s_addc_u32 s21, s35, s21
	s_waitcnt lgkmcnt(0)
	v_pk_add_f32 v[6:7], v[30:31], v[0:1] op_sel_hi:[1,0] neg_lo:[0,1] neg_hi:[0,1]
	s_nop 0
	v_pk_mul_f32 v[0:1], v[0:1], v[6:7] op_sel:[1,0]
	s_nop 0
	v_pk_fma_f32 v[0:1], v[58:59], v[0:1], v[66:67]
	s_nop 0
	v_mul_f32_e32 v6, 0xbfb8aa3b, v0
	v_mul_f32_e32 v7, 0xbfb8aa3b, v1
	v_exp_f32_e32 v6, v6
	v_exp_f32_e32 v7, v7
	v_add_f32_e32 v6, 1.0, v6
	v_add_f32_e32 v7, 1.0, v7
	v_rcp_f32_e32 v6, v6
	v_rcp_f32_e32 v7, v7
	s_nop 0
	v_pk_mul_f32 v[0:1], v[0:1], v[6:7]
	s_nop 0
	v_pk_mul_f32 v[0:1], v[0:1], v[4:5]
	s_nop 0
	v_cvt_pk_bf16_f32 v4, v0, v1
	v_lshl_add_u64 v[0:1], s[20:21], 0, v[14:15]
	v_add_co_u32_e32 v0, vcc, s25, v0
	s_lshl_b64 s[20:21], s[46:47], 12
	s_nop 0
	v_addc_co_u32_e32 v1, vcc, 0, v1, vcc
	global_store_dword v[0:1], v4, off offset:2048 sc1
	v_pk_add_f32 v[4:5], v[28:29], v[2:3] op_sel_hi:[1,0] neg_lo:[0,1] neg_hi:[0,1]
	v_mov_b32_e32 v2, v3
	v_pk_mul_f32 v[2:3], v[2:3], v[4:5] op_sel_hi:[0,1]
	v_pk_fma_f32 v[2:3], v[58:59], v[2:3], v[66:67]
	v_lshlrev_b32_e32 v0, 16, v92
	v_mul_f32_e32 v4, 0xbfb8aa3b, v2
	v_mul_f32_e32 v5, 0xbfb8aa3b, v3
	v_exp_f32_e32 v4, v4
	v_exp_f32_e32 v5, v5
	v_and_b32_e32 v1, 0xffff0000, v92
	s_add_u32 s20, s34, s20
	v_add_f32_e32 v4, 1.0, v4
	v_add_f32_e32 v5, 1.0, v5
	v_rcp_f32_e32 v4, v4
	v_rcp_f32_e32 v5, v5
	s_addc_u32 s21, s35, s21
	v_pk_mul_f32 v[2:3], v[2:3], v[4:5]
	s_nop 0
	v_pk_mul_f32 v[0:1], v[2:3], v[0:1]
	v_lshlrev_b32_e32 v4, 16, v90
	v_cvt_pk_bf16_f32 v2, v0, v1
	v_lshl_add_u64 v[0:1], s[20:21], 0, v[14:15]
	v_add_co_u32_e32 v0, vcc, s25, v0
	s_lshl_b64 s[20:21], s[44:45], 12
	s_nop 0
	v_addc_co_u32_e32 v1, vcc, 0, v1, vcc
	global_store_dword v[0:1], v2, off offset:2048 sc1
	ds_read_b128 v[0:3], v15 offset:2272
	v_and_b32_e32 v5, 0xffff0000, v90
	s_add_u32 s20, s34, s20
	s_addc_u32 s21, s35, s21
	s_waitcnt lgkmcnt(0)
; __device__ __forceinline__ unsigned cvtpk(float lo, float hi) { f32x2 v = {lo, hi}; bf16x2_t b = __builtin_convertvector(v, bf16x2_t); return __builtin_bit_cast(unsigned, b); }
; __device__ __forceinline__ float silu_f(float v) { return v * __builtin_amdgcn_rcpf(1.0f + __builtin_amdgcn_exp2f(-v * LOG2E)); }
; __device__ __forceinline__ void conv_unit(unsigned char* ws, LAS unsigned char* lds, int t0) {
;     ...
;     const f32x2 lg = *(const f32x2*)(ln_g + c0), lb = *(const f32x2*)(ln_b + c0);
; #pragma unroll
;     for (int t = 0; t < 32; ++t) {
;         const float mean = stat[t * 2], rstd = stat[t * 2 + 1];
;         const float v0 = (a0[t] - mean) * rstd * lg[0] + lb[0], v1 = (a1[t] - mean) * rstd * lg[1] + lb[1];
;         const unsigned gc = gcv[t];
;         *(unsigned*)(MIX + (size_t)(t0 + t) * DM + ATTW + c0) = cvtpk(silu_f(v0) * bf_lo(gc), silu_f(v1) * bf_hi(gc));
;     }
;     __syncthreads();
; __global__ void __launch_bounds__(512, 2) fwd_kernel(Args args) {
;     ...
;                 for (int cu = j; cu < SEQ / 32; cu += 120) conv_unit(ws, lds, 32 * cu);
	v_pk_add_f32 v[6:7], v[26:27], v[0:1] op_sel_hi:[1,0] neg_lo:[0,1] neg_hi:[0,1]
	s_nop 0
	v_pk_mul_f32 v[0:1], v[0:1], v[6:7] op_sel:[1,0]
	s_nop 0
	v_pk_fma_f32 v[0:1], v[58:59], v[0:1], v[66:67]
	s_nop 0
	v_mul_f32_e32 v6, 0xbfb8aa3b, v0
	v_mul_f32_e32 v7, 0xbfb8aa3b, v1
	v_exp_f32_e32 v6, v6
	v_exp_f32_e32 v7, v7
	v_add_f32_e32 v6, 1.0, v6
	v_add_f32_e32 v7, 1.0, v7
	v_rcp_f32_e32 v6, v6
	v_rcp_f32_e32 v7, v7
	s_nop 0
	v_pk_mul_f32 v[0:1], v[0:1], v[6:7]
	s_nop 0
	v_pk_mul_f32 v[0:1], v[0:1], v[4:5]
	s_nop 0
	v_cvt_pk_bf16_f32 v4, v0, v1
	v_lshl_add_u64 v[0:1], s[20:21], 0, v[14:15]
	v_add_co_u32_e32 v0, vcc, s25, v0
	s_lshl_b64 s[20:21], s[42:43], 12
	s_nop 0
	v_addc_co_u32_e32 v1, vcc, 0, v1, vcc
	global_store_dword v[0:1], v4, off offset:2048 sc1
	v_pk_add_f32 v[4:5], v[24:25], v[2:3] op_sel_hi:[1,0] neg_lo:[0,1] neg_hi:[0,1]
	v_mov_b32_e32 v2, v3
	v_pk_mul_f32 v[2:3], v[2:3], v[4:5] op_sel_hi:[0,1]
	v_pk_fma_f32 v[2:3], v[58:59], v[2:3], v[66:67]
	v_lshlrev_b32_e32 v0, 16, v91
	v_mul_f32_e32 v4, 0xbfb8aa3b, v2
	v_mul_f32_e32 v5, 0xbfb8aa3b, v3
	v_exp_f32_e32 v4, v4
	v_exp_f32_e32 v5, v5
	v_and_b32_e32 v1, 0xffff0000, v91
	s_add_u32 s20, s34, s20
	v_add_f32_e32 v4, 1.0, v4
	v_add_f32_e32 v5, 1.0, v5
	v_rcp_f32_e32 v4, v4
	v_rcp_f32_e32 v5, v5
	s_addc_u32 s21, s35, s21
	v_pk_mul_f32 v[2:3], v[2:3], v[4:5]
	s_nop 0
	v_pk_mul_f32 v[0:1], v[2:3], v[0:1]
	v_lshlrev_b32_e32 v4, 16, v89
	v_cvt_pk_bf16_f32 v2, v0, v1
	v_lshl_add_u64 v[0:1], s[20:21], 0, v[14:15]
	v_add_co_u32_e32 v0, vcc, s25, v0
	s_lshl_b64 s[20:21], s[40:41], 12
	s_nop 0
	v_addc_co_u32_e32 v1, vcc, 0, v1, vcc
	global_store_dword v[0:1], v2, off offset:2048 sc1
	ds_read_b128 v[0:3], v15 offset:2288
	v_and_b32_e32 v5, 0xffff0000, v89
	s_add_u32 s20, s34, s20
	s_addc_u32 s21, s35, s21
	s_lshl_b64 s[18:19], s[18:19], 12
	s_waitcnt lgkmcnt(0)
	v_pk_add_f32 v[6:7], v[22:23], v[0:1] op_sel_hi:[1,0] neg_lo:[0,1] neg_hi:[0,1]
	s_add_u32 s18, s34, s18
	v_pk_mul_f32 v[0:1], v[0:1], v[6:7] op_sel:[1,0]
	s_addc_u32 s19, s35, s19
	v_pk_fma_f32 v[0:1], v[58:59], v[0:1], v[66:67]
	s_add_i32 s38, s38, 0x3c0000
	v_mul_f32_e32 v6, 0xbfb8aa3b, v0
	v_mul_f32_e32 v7, 0xbfb8aa3b, v1
	v_exp_f32_e32 v6, v6
	v_exp_f32_e32 v7, v7
	s_addk_i32 s24, 0xf00
	s_cmpk_gt_i32 s3, 0x87
	v_add_f32_e32 v6, 1.0, v6
	v_add_f32_e32 v7, 1.0, v7
	v_rcp_f32_e32 v6, v6
	v_rcp_f32_e32 v7, v7
	s_nop 0
	v_pk_mul_f32 v[0:1], v[0:1], v[6:7]
	s_nop 0
	v_pk_mul_f32 v[0:1], v[0:1], v[4:5]
	s_nop 0
	v_cvt_pk_bf16_f32 v4, v0, v1
	v_lshl_add_u64 v[0:1], s[20:21], 0, v[14:15]
	v_add_co_u32_e32 v0, vcc, s25, v0
	s_nop 1
	v_addc_co_u32_e32 v1, vcc, 0, v1, vcc
	global_store_dword v[0:1], v4, off offset:2048 sc1
	v_pk_add_f32 v[4:5], v[20:21], v[2:3] op_sel_hi:[1,0] neg_lo:[0,1] neg_hi:[0,1]
	v_mov_b32_e32 v2, v3
	v_pk_mul_f32 v[2:3], v[2:3], v[4:5] op_sel_hi:[0,1]
	v_pk_fma_f32 v[2:3], v[58:59], v[2:3], v[66:67]
	v_lshlrev_b32_e32 v0, 16, v88
	v_mul_f32_e32 v4, 0xbfb8aa3b, v2
	v_mul_f32_e32 v5, 0xbfb8aa3b, v3
	v_exp_f32_e32 v4, v4
	v_exp_f32_e32 v5, v5
	v_and_b32_e32 v1, 0xffff0000, v88
	v_add_f32_e32 v4, 1.0, v4
	v_add_f32_e32 v5, 1.0, v5
	v_rcp_f32_e32 v4, v4
	v_rcp_f32_e32 v5, v5
	s_nop 0
	v_pk_mul_f32 v[2:3], v[2:3], v[4:5]
	s_nop 0
	v_pk_mul_f32 v[0:1], v[2:3], v[0:1]
	s_nop 0
	v_cvt_pk_bf16_f32 v2, v0, v1
	v_lshl_add_u64 v[0:1], s[18:19], 0, v[14:15]
	v_add_co_u32_e32 v0, vcc, 0xac00000, v0
	s_nop 1
	v_addc_co_u32_e32 v1, vcc, 0, v1, vcc
	global_store_dword v[0:1], v2, off offset:2048 sc1
	s_barrier
	s_cbranch_scc1 .LBB0_566

; #define LAS __attribute__((address_space(3)))
; __device__ __forceinline__ void transpose_item(const float* W, int N, bf16_t* WT, int k0, int n0, bool is_in, LAS float* scr, int lane) {
;     const int lr = lane >> 4, lc = (lane & 15) * 4;
;     f32x4 v[16];
; #pragma unroll
;     for (int i = 0; i < 16; ++i) v[i] = __builtin_nontemporal_load((const f32x4*)(W + (size_t)(k0 + 4 * i + lr) * N + n0 + lc));
; #pragma unroll
;     for (int i = 0; i < 16; ++i) { LAS float* d = scr + (4 * i + lr) * 65 + lc; d[0] = v[i][0]; d[1] = v[i][1]; d[2] = v[i][2]; d[3] = v[i][3]; }
; __global__ void __launch_bounds__(512, 2) fwd_kernel(Args args) {
;     ...
;                     for (int it = (j - 16) * 8 + wave; it < 32 * (DM / 64); it += 104 * 8) { const int kb = it / (DM / 64), nb = it % (DM / 64); transpose_item(w_out, DM, WO, kb * 64, nb * 64, false, scr, lane); }
.LBB0_569:
	s_ashr_i32 s5, s3, 31
	s_lshr_b32 s5, s5, 27
	s_add_i32 s5, s3, s5
	s_ashr_i32 s5, s5, 5
	s_lshl_b32 s8, s5, 6
	s_lshl_b32 s5, s5, 11
	v_or_b32_e32 v40, s8, v4
	s_sub_i32 s10, s4, s5
	v_or_b32_e32 v42, 4, v40
	v_or_b32_e32 v44, 8, v40
	v_or_b32_e32 v46, 12, v40
	v_or_b32_e32 v48, 16, v40
	v_or_b32_e32 v50, 20, v40
	v_or_b32_e32 v52, 24, v40
	v_or_b32_e32 v54, 28, v40
	s_ashr_i32 s11, s10, 31
	v_ashrrev_i32_e32 v41, 31, v40
	v_or_b32_e32 v56, 32, v40
	v_or_b32_e32 v58, 36, v40
	v_or_b32_e32 v60, 40, v40
	v_or_b32_e32 v62, 44, v40
	v_or_b32_e32 v64, 48, v40
	v_or_b32_e32 v66, 52, v40
	v_or_b32_e32 v68, 56, v40
	v_or_b32_e32 v70, 60, v40
	v_add_u32_e32 v72, s10, v5
	v_ashrrev_i32_e32 v43, 31, v42
	v_ashrrev_i32_e32 v45, 31, v44
	v_ashrrev_i32_e32 v47, 31, v46
	v_ashrrev_i32_e32 v49, 31, v48
	v_ashrrev_i32_e32 v51, 31, v50
	v_ashrrev_i32_e32 v53, 31, v52
	v_ashrrev_i32_e32 v55, 31, v54
	s_ashr_i32 s9, s8, 31
	v_lshl_add_u64 v[74:75], s[10:11], 2, v[0:1]
	v_lshlrev_b64 v[40:41], 13, v[40:41]
	v_ashrrev_i32_e32 v57, 31, v56
	v_ashrrev_i32_e32 v59, 31, v58
	v_ashrrev_i32_e32 v61, 31, v60
	v_ashrrev_i32_e32 v63, 31, v62
	v_ashrrev_i32_e32 v65, 31, v64
	v_ashrrev_i32_e32 v67, 31, v66
	v_ashrrev_i32_e32 v69, 31, v68
	v_ashrrev_i32_e32 v71, 31, v70
	v_ashrrev_i32_e32 v73, 31, v72
	v_add_u32_e32 v76, 8, v72
	v_add_u32_e32 v78, 16, v72
	v_add_u32_e32 v80, 24, v72
	v_add_u32_e32 v82, 32, v72
	v_add_u32_e32 v84, 40, v72
	v_add_u32_e32 v86, 48, v72
	v_add_u32_e32 v88, 56, v72
	v_lshlrev_b64 v[90:91], 13, v[42:43]
	v_lshlrev_b64 v[44:45], 13, v[44:45]
	v_lshlrev_b64 v[46:47], 13, v[46:47]
	v_lshlrev_b64 v[48:49], 13, v[48:49]
	v_lshlrev_b64 v[50:51], 13, v[50:51]
	v_lshlrev_b64 v[52:53], 13, v[52:53]
	v_lshlrev_b64 v[54:55], 13, v[54:55]
	v_lshl_add_u64 v[104:105], s[8:9], 1, v[2:3]
	v_lshl_add_u64 v[40:41], v[74:75], 0, v[40:41]
	v_lshlrev_b64 v[56:57], 13, v[56:57]
	v_lshlrev_b64 v[58:59], 13, v[58:59]
	v_lshlrev_b64 v[60:61], 13, v[60:61]
	v_lshlrev_b64 v[62:63], 13, v[62:63]
	v_lshlrev_b64 v[64:65], 13, v[64:65]
	v_lshlrev_b64 v[66:67], 13, v[66:67]
	v_lshlrev_b64 v[68:69], 13, v[68:69]
	v_lshlrev_b64 v[70:71], 13, v[70:71]
	v_lshlrev_b64 v[72:73], 12, v[72:73]
	v_ashrrev_i32_e32 v77, 31, v76
	v_ashrrev_i32_e32 v79, 31, v78
	v_ashrrev_i32_e32 v81, 31, v80
	v_ashrrev_i32_e32 v83, 31, v82
	v_ashrrev_i32_e32 v85, 31, v84
	v_ashrrev_i32_e32 v87, 31, v86
	v_ashrrev_i32_e32 v89, 31, v88
	v_lshl_add_u64 v[90:91], v[74:75], 0, v[90:91]
	v_lshl_add_u64 v[92:93], v[74:75], 0, v[44:45]
	v_lshl_add_u64 v[94:95], v[74:75], 0, v[46:47]
	v_lshl_add_u64 v[96:97], v[74:75], 0, v[48:49]
	v_lshl_add_u64 v[98:99], v[74:75], 0, v[50:51]
	v_lshl_add_u64 v[100:101], v[74:75], 0, v[52:53]
	v_lshl_add_u64 v[102:103], v[74:75], 0, v[54:55]
	global_load_dwordx4 v[40:43], v[40:41], off nt
	v_lshl_add_u64 v[106:107], v[74:75], 0, v[56:57]
	v_lshl_add_u64 v[108:109], v[74:75], 0, v[58:59]
	v_lshl_add_u64 v[110:111], v[74:75], 0, v[60:61]
	v_lshl_add_u64 v[112:113], v[74:75], 0, v[62:63]
	v_lshl_add_u64 v[114:115], v[74:75], 0, v[64:65]
	v_lshl_add_u64 v[116:117], v[74:75], 0, v[66:67]
	v_lshl_add_u64 v[118:119], v[74:75], 0, v[68:69]
	v_lshl_add_u64 v[120:121], v[74:75], 0, v[70:71]
	v_lshl_add_u64 v[122:123], v[104:105], 0, v[72:73]
	v_lshlrev_b64 v[124:125], 12, v[76:77]
	v_lshlrev_b64 v[126:127], 12, v[78:79]
	v_lshlrev_b64 v[128:129], 12, v[80:81]
	v_lshlrev_b64 v[130:131], 12, v[82:83]
	v_lshlrev_b64 v[132:133], 12, v[84:85]
	v_lshlrev_b64 v[134:135], 12, v[86:87]
	v_lshlrev_b64 v[136:137], 12, v[88:89]
	global_load_dwordx4 v[44:47], v[90:91], off nt
	global_load_dwordx4 v[48:51], v[92:93], off nt
	global_load_dwordx4 v[52:55], v[94:95], off nt
	global_load_dwordx4 v[56:59], v[96:97], off nt
	global_load_dwordx4 v[60:63], v[98:99], off nt
	global_load_dwordx4 v[64:67], v[100:101], off nt
	global_load_dwordx4 v[68:71], v[102:103], off nt
	global_load_dwordx4 v[72:75], v[106:107], off nt
	global_load_dwordx4 v[76:79], v[108:109], off nt
	global_load_dwordx4 v[80:83], v[110:111], off nt
	global_load_dwordx4 v[84:87], v[112:113], off nt
	global_load_dwordx4 v[88:91], v[114:115], off nt
	global_load_dwordx4 v[92:95], v[116:117], off nt
	global_load_dwordx4 v[96:99], v[118:119], off nt
	global_load_dwordx4 v[100:103], v[120:121], off nt
	s_waitcnt vmcnt(15)
	ds_write2_b32 v7, v40, v41 offset1:1
	ds_write2_b32 v7, v42, v43 offset0:2 offset1:3
	s_waitcnt vmcnt(14)
	ds_write2_b32 v8, v44, v45 offset1:1
	ds_write2_b32 v9, v46, v47 offset1:1
	s_waitcnt vmcnt(13)
	ds_write2_b32 v10, v48, v49 offset1:1
	ds_write2_b32 v11, v50, v51 offset1:1
	s_waitcnt vmcnt(12)
	ds_write2_b32 v12, v52, v53 offset1:1
	ds_write2_b32 v13, v54, v55 offset1:1
	s_waitcnt vmcnt(11)
	ds_write2_b32 v14, v56, v57 offset1:1
	ds_write2_b32 v15, v58, v59 offset1:1
	s_waitcnt vmcnt(10)
; #define LAS __attribute__((address_space(3)))
; __device__ __forceinline__ unsigned cvtpk(float lo, float hi) { f32x2 v = {lo, hi}; bf16x2_t b = __builtin_convertvector(v, bf16x2_t); return __builtin_bit_cast(unsigned, b); }
; __device__ __forceinline__ void transpose_item(const float* W, int N, bf16_t* WT, int k0, int n0, bool is_in, LAS float* scr, int lane) {
;     ...
;     for (int i = 0; i < 16; ++i) { LAS float* d = scr + (4 * i + lr) * 65 + lc; d[0] = v[i][0]; d[1] = v[i][1]; d[2] = v[i][2]; d[3] = v[i][3]; }
;     asm volatile("s_waitcnt lgkmcnt(0)" ::: "memory");
;     const int c = lane & 7;
; #pragma unroll
;     for (int j = 0; j < 8; ++j) {
;         const int n = (lane >> 3) + 8 * j; const LAS float* s = scr + (8 * c) * 65 + n;
;         u32x4 o; o.x = cvtpk(s[0 * 65], s[1 * 65]); o.y = cvtpk(s[2 * 65], s[3 * 65]); o.z = cvtpk(s[4 * 65], s[5 * 65]); o.w = cvtpk(s[6 * 65], s[7 * 65]);
;         const int dr = is_in ? win_dest_row(n0 + n) : (n0 + n);
;         *(u32x4*)(WT + (size_t)dr * DM + k0 + 8 * c) = o;
;     }
; __global__ void __launch_bounds__(512, 2) fwd_kernel(Args args) {
;     ...
;                     for (int it = (j - 16) * 8 + wave; it < 32 * (DM / 64); it += 104 * 8) { const int kb = it / (DM / 64), nb = it % (DM / 64); transpose_item(w_out, DM, WO, kb * 64, nb * 64, false, scr, lane); }
	ds_write2_b32 v16, v60, v61 offset1:1
	ds_write2_b32 v17, v62, v63 offset1:1
	s_waitcnt vmcnt(9)
	ds_write2_b32 v18, v64, v65 offset1:1
	ds_write2_b32 v19, v66, v67 offset1:1
	s_waitcnt vmcnt(8)
	ds_write2_b32 v20, v68, v69 offset1:1
	ds_write2_b32 v21, v70, v71 offset1:1
	s_waitcnt vmcnt(7)
	ds_write2_b32 v22, v72, v73 offset1:1
	ds_write2_b32 v23, v74, v75 offset1:1
	s_waitcnt vmcnt(6)
	ds_write2_b32 v24, v76, v77 offset1:1
	ds_write2_b32 v25, v78, v79 offset1:1
	s_waitcnt vmcnt(5)
	ds_write2_b32 v26, v80, v81 offset1:1
	ds_write2_b32 v27, v82, v83 offset1:1
	s_waitcnt vmcnt(4)
	ds_write2_b32 v28, v84, v85 offset1:1
	ds_write2_b32 v29, v86, v87 offset1:1
	s_waitcnt vmcnt(3)
	ds_write2_b32 v30, v88, v89 offset1:1
	ds_write2_b32 v31, v90, v91 offset1:1
	s_waitcnt vmcnt(2)
	ds_write2_b32 v32, v92, v93 offset1:1
	ds_write2_b32 v33, v94, v95 offset1:1
	s_waitcnt vmcnt(1)
	ds_write2_b32 v34, v96, v97 offset1:1
	ds_write2_b32 v35, v98, v99 offset1:1
	s_waitcnt vmcnt(0)
	ds_write2_b32 v36, v100, v101 offset1:1
	ds_write2_b32 v37, v102, v103 offset1:1
	s_waitcnt lgkmcnt(0)
	ds_read2_b32 v[44:45], v6 offset0:65 offset1:73
	ds_read2_b32 v[46:47], v6 offset1:8
	ds_read2_b32 v[48:49], v6 offset0:130 offset1:138
	ds_read2_b32 v[50:51], v6 offset0:195 offset1:203
	ds_read2_b32 v[52:53], v38 offset0:4 offset1:12
	ds_read2_b32 v[54:55], v38 offset0:69 offset1:77
	ds_read2_b32 v[56:57], v38 offset0:134 offset1:142
	ds_read2_b32 v[58:59], v38 offset0:199 offset1:207
	ds_read2_b32 v[60:61], v6 offset0:81 offset1:89
	ds_read2_b32 v[62:63], v6 offset0:16 offset1:24
	ds_read2_b32 v[64:65], v6 offset0:146 offset1:154
	ds_read2_b32 v[66:67], v6 offset0:211 offset1:219
	ds_read2_b32 v[68:69], v38 offset0:20 offset1:28
	ds_read2_b32 v[70:71], v38 offset0:85 offset1:93
	ds_read2_b32 v[72:73], v38 offset0:150 offset1:158
	ds_read2_b32 v[74:75], v38 offset0:215 offset1:223
	ds_read2_b32 v[76:77], v6 offset0:32 offset1:40
	ds_read2_b32 v[78:79], v6 offset0:97 offset1:105
	ds_read2_b32 v[80:81], v6 offset0:162 offset1:170
	ds_read2_b32 v[82:83], v6 offset0:227 offset1:235
	ds_read2_b32 v[84:85], v38 offset0:36 offset1:44
	ds_read2_b32 v[86:87], v38 offset0:101 offset1:109
	ds_read2_b32 v[88:89], v38 offset0:166 offset1:174
	ds_read2_b32 v[90:91], v38 offset0:231 offset1:239
	ds_read2_b32 v[92:93], v6 offset0:48 offset1:56
	ds_read2_b32 v[94:95], v6 offset0:113 offset1:121
	ds_read2_b32 v[96:97], v6 offset0:178 offset1:186
	ds_read2_b32 v[98:99], v6 offset0:243 offset1:251
	ds_read2_b32 v[100:101], v38 offset0:52 offset1:60
	ds_read2_b32 v[102:103], v38 offset0:117 offset1:125
	ds_read2_b32 v[118:119], v38 offset0:182 offset1:190
	ds_read2_b32 v[120:121], v38 offset0:247 offset1:255
	s_waitcnt lgkmcnt(14)
	v_cvt_pk_bf16_f32 v40, v46, v44
	v_cvt_pk_bf16_f32 v41, v48, v50
	v_cvt_pk_bf16_f32 v42, v52, v54
	v_cvt_pk_bf16_f32 v43, v56, v58
	v_lshl_add_u64 v[106:107], v[104:105], 0, v[124:125]
	v_lshl_add_u64 v[108:109], v[104:105], 0, v[126:127]
	v_lshl_add_u64 v[110:111], v[104:105], 0, v[128:129]
	v_lshl_add_u64 v[112:113], v[104:105], 0, v[130:131]
	v_lshl_add_u64 v[114:115], v[104:105], 0, v[132:133]
	v_lshl_add_u64 v[116:117], v[104:105], 0, v[134:135]
	v_lshl_add_u64 v[104:105], v[104:105], 0, v[136:137]
	v_cvt_pk_bf16_f32 v44, v47, v45
	v_cvt_pk_bf16_f32 v45, v49, v51
	v_cvt_pk_bf16_f32 v46, v53, v55
	v_cvt_pk_bf16_f32 v47, v57, v59
	v_cvt_pk_bf16_f32 v48, v62, v60
	v_cvt_pk_bf16_f32 v49, v64, v66
	v_cvt_pk_bf16_f32 v50, v68, v70
	v_cvt_pk_bf16_f32 v51, v72, v74
	v_cvt_pk_bf16_f32 v52, v63, v61
	v_cvt_pk_bf16_f32 v53, v65, v67
	v_cvt_pk_bf16_f32 v54, v69, v71
	v_cvt_pk_bf16_f32 v55, v73, v75
	v_cvt_pk_bf16_f32 v56, v76, v78
	s_waitcnt lgkmcnt(12)
	v_cvt_pk_bf16_f32 v57, v80, v82
	s_waitcnt lgkmcnt(10)
	v_cvt_pk_bf16_f32 v58, v84, v86
	s_waitcnt lgkmcnt(8)
	v_cvt_pk_bf16_f32 v59, v88, v90
	v_cvt_pk_bf16_f32 v60, v77, v79
	v_cvt_pk_bf16_f32 v61, v81, v83
	v_cvt_pk_bf16_f32 v62, v85, v87
	v_cvt_pk_bf16_f32 v63, v89, v91
	s_waitcnt lgkmcnt(6)
	v_cvt_pk_bf16_f32 v64, v92, v94
	s_waitcnt lgkmcnt(4)
	v_cvt_pk_bf16_f32 v65, v96, v98
	s_waitcnt lgkmcnt(2)
	v_cvt_pk_bf16_f32 v66, v100, v102
	s_waitcnt lgkmcnt(0)
	v_cvt_pk_bf16_f32 v67, v118, v120
	v_cvt_pk_bf16_f32 v68, v93, v95
	v_cvt_pk_bf16_f32 v69, v97, v99
	v_cvt_pk_bf16_f32 v70, v101, v103
	v_cvt_pk_bf16_f32 v71, v119, v121
	global_store_dwordx4 v[122:123], v[40:43], off sc1
	global_store_dwordx4 v[106:107], v[44:47], off sc1
	global_store_dwordx4 v[108:109], v[48:51], off sc1
	global_store_dwordx4 v[110:111], v[52:55], off sc1
	global_store_dwordx4 v[112:113], v[56:59], off sc1
	global_store_dwordx4 v[114:115], v[60:63], off sc1
	global_store_dwordx4 v[116:117], v[64:67], off sc1
	global_store_dwordx4 v[104:105], v[68:71], off sc1
	s_waitcnt lgkmcnt(0)
	s_add_i32 s6, s3, 0x340
	s_add_i32 s4, s4, 0xd000
	s_cmpk_gt_i32 s3, 0xbf
	s_mov_b32 s3, s6
	s_cbranch_scc0 .LBB0_569

; __device__ __forceinline__ void attn_unit(unsigned char* ws, const float* sub_g, LAS unsigned char* lds, int h, int qb, float negM, float lam) {
;     ...
;     __syncthreads();
;     if (map == 0) {
;         float ss = 0.f;
; #pragma unroll
;         for (int b = 0; b < 4; ++b)
; #pragma unroll
;             for (int r = 0; r < 16; ++r) { const float v = o[b][r] * inv - xw[(b * 16 + r) * 64 + lane]; o[b][r] = v; ss += v * v; }
;         ss += __shfl_xor(ss, 32);
;         const float rs = __builtin_amdgcn_rsqf(ss * (1.0f / VD) + EPS) * (1.0f - LAM_INIT);
.LBB0_836:
	s_cmpk_gt_u32 s25, 0xff
	s_waitcnt vmcnt(0) lgkmcnt(0)
	s_barrier
	s_cbranch_scc1 .LBB0_829
	ds_read2st64_b32 v[82:83], v80 offset1:1
	ds_read2st64_b32 v[92:93], v80 offset0:2 offset1:3
	ds_read2st64_b32 v[94:95], v80 offset0:4 offset1:5
	ds_read2st64_b32 v[96:97], v80 offset0:6 offset1:7
	ds_read2st64_b32 v[98:99], v80 offset0:8 offset1:9
	ds_read2st64_b32 v[100:101], v80 offset0:10 offset1:11
	ds_read2st64_b32 v[102:103], v80 offset0:12 offset1:13
	ds_read2st64_b32 v[104:105], v80 offset0:14 offset1:15
	ds_read2st64_b32 v[140:141], v80 offset0:16 offset1:17
	ds_read2st64_b32 v[142:143], v80 offset0:18 offset1:19
	ds_read2st64_b32 v[144:145], v80 offset0:20 offset1:21
	ds_read2st64_b32 v[146:147], v80 offset0:22 offset1:23
	ds_read2st64_b32 v[184:185], v80 offset0:24 offset1:25
	ds_read2st64_b32 v[186:187], v80 offset0:26 offset1:27
	ds_read2st64_b32 v[188:189], v80 offset0:28 offset1:29
	ds_read2st64_b32 v[190:191], v80 offset0:30 offset1:31
	ds_read2st64_b32 v[192:193], v80 offset0:32 offset1:33
	ds_read2st64_b32 v[194:195], v80 offset0:34 offset1:35
	ds_read2st64_b32 v[196:197], v80 offset0:36 offset1:37
	ds_read2st64_b32 v[198:199], v80 offset0:38 offset1:39
	ds_read2st64_b32 v[200:201], v80 offset0:40 offset1:41
	ds_read2st64_b32 v[202:203], v80 offset0:42 offset1:43
	ds_read2st64_b32 v[204:205], v80 offset0:44 offset1:45
	ds_read2st64_b32 v[206:207], v80 offset0:46 offset1:47
	ds_read2st64_b32 v[84:85], v80 offset0:58 offset1:59
	ds_read2st64_b32 v[208:209], v80 offset0:48 offset1:49
	ds_read2st64_b32 v[210:211], v80 offset0:50 offset1:51
	ds_read2st64_b32 v[214:215], v80 offset0:52 offset1:53
	ds_read2st64_b32 v[216:217], v80 offset0:54 offset1:55
	ds_read2st64_b32 v[88:89], v80 offset0:60 offset1:61
	ds_read2st64_b32 v[218:219], v80 offset0:56 offset1:57
	ds_read2st64_b32 v[80:81], v80 offset0:62 offset1:63
	s_waitcnt lgkmcnt(7)
	v_pk_fma_f32 v[86:87], v[26:27], v[90:91], v[84:85] op_sel_hi:[1,0,1] neg_lo:[0,0,1] neg_hi:[0,0,1]
	s_lshl_b32 s8, s24, 1
	s_waitcnt lgkmcnt(2)
	v_pk_fma_f32 v[84:85], v[28:29], v[90:91], v[88:89] op_sel_hi:[1,0,1] neg_lo:[0,0,1] neg_hi:[0,0,1]
	v_pk_mul_f32 v[108:109], v[86:87], v[86:87]
	s_waitcnt lgkmcnt(0)
	v_pk_fma_f32 v[88:89], v[30:31], v[90:91], v[80:81] op_sel_hi:[1,0,1] neg_lo:[0,0,1] neg_hi:[0,0,1]
	v_add_u32_e32 v91, s29, v155
	v_pk_fma_f32 v[106:107], v[66:67], v[90:91], v[92:93] op_sel_hi:[1,0,1] neg_lo:[0,0,1] neg_hi:[0,0,1]
	v_pk_fma_f32 v[114:115], v[64:65], v[90:91], v[82:83] op_sel_hi:[1,0,1] neg_lo:[0,0,1] neg_hi:[0,0,1]
	global_load_dwordx4 v[80:83], v[132:133], off
	global_load_dwordx4 v[64:67], v[132:133], off offset:32
	v_pk_mul_f32 v[224:225], v[114:115], v[114:115]
	v_pk_mul_f32 v[222:223], v[106:107], v[106:107]
	v_pk_fma_f32 v[112:113], v[70:71], v[90:91], v[96:97] op_sel_hi:[1,0,1] neg_lo:[0,0,1] neg_hi:[0,0,1]
	v_pk_fma_f32 v[120:121], v[68:69], v[90:91], v[94:95] op_sel_hi:[1,0,1] neg_lo:[0,0,1] neg_hi:[0,0,1]
	v_pk_fma_f32 v[118:119], v[74:75], v[90:91], v[100:101] op_sel_hi:[1,0,1] neg_lo:[0,0,1] neg_hi:[0,0,1]
	v_pk_fma_f32 v[124:125], v[72:73], v[90:91], v[98:99] op_sel_hi:[1,0,1] neg_lo:[0,0,1] neg_hi:[0,0,1]
	v_pk_fma_f32 v[122:123], v[78:79], v[90:91], v[104:105] op_sel_hi:[1,0,1] neg_lo:[0,0,1] neg_hi:[0,0,1]
	v_pk_fma_f32 v[126:127], v[76:77], v[90:91], v[102:103] op_sel_hi:[1,0,1] neg_lo:[0,0,1] neg_hi:[0,0,1]
	v_pk_fma_f32 v[76:77], v[50:51], v[90:91], v[142:143] op_sel_hi:[1,0,1] neg_lo:[0,0,1] neg_hi:[0,0,1]
	v_pk_fma_f32 v[78:79], v[48:49], v[90:91], v[140:141] op_sel_hi:[1,0,1] neg_lo:[0,0,1] neg_hi:[0,0,1]
	v_pk_fma_f32 v[92:93], v[54:55], v[90:91], v[146:147] op_sel_hi:[1,0,1] neg_lo:[0,0,1] neg_hi:[0,0,1]
	v_pk_fma_f32 v[94:95], v[52:53], v[90:91], v[144:145] op_sel_hi:[1,0,1] neg_lo:[0,0,1] neg_hi:[0,0,1]
	v_pk_fma_f32 v[96:97], v[58:59], v[90:91], v[186:187] op_sel_hi:[1,0,1] neg_lo:[0,0,1] neg_hi:[0,0,1]
	v_pk_fma_f32 v[98:99], v[56:57], v[90:91], v[184:185] op_sel_hi:[1,0,1] neg_lo:[0,0,1] neg_hi:[0,0,1]
	v_pk_fma_f32 v[100:101], v[62:63], v[90:91], v[190:191] op_sel_hi:[1,0,1] neg_lo:[0,0,1] neg_hi:[0,0,1]
	v_pk_fma_f32 v[102:103], v[60:61], v[90:91], v[188:189] op_sel_hi:[1,0,1] neg_lo:[0,0,1] neg_hi:[0,0,1]
	v_pk_fma_f32 v[34:35], v[34:35], v[90:91], v[194:195] op_sel_hi:[1,0,1] neg_lo:[0,0,1] neg_hi:[0,0,1]
	v_pk_fma_f32 v[104:105], v[32:33], v[90:91], v[192:193] op_sel_hi:[1,0,1] neg_lo:[0,0,1] neg_hi:[0,0,1]
	v_pk_fma_f32 v[38:39], v[38:39], v[90:91], v[198:199] op_sel_hi:[1,0,1] neg_lo:[0,0,1] neg_hi:[0,0,1]
	v_pk_fma_f32 v[36:37], v[36:37], v[90:91], v[196:197] op_sel_hi:[1,0,1] neg_lo:[0,0,1] neg_hi:[0,0,1]
	v_pk_fma_f32 v[42:43], v[42:43], v[90:91], v[202:203] op_sel_hi:[1,0,1] neg_lo:[0,0,1] neg_hi:[0,0,1]
	v_pk_fma_f32 v[40:41], v[40:41], v[90:91], v[200:201] op_sel_hi:[1,0,1] neg_lo:[0,0,1] neg_hi:[0,0,1]
	v_pk_fma_f32 v[46:47], v[46:47], v[90:91], v[206:207] op_sel_hi:[1,0,1] neg_lo:[0,0,1] neg_hi:[0,0,1]
	v_pk_fma_f32 v[44:45], v[44:45], v[90:91], v[204:205] op_sel_hi:[1,0,1] neg_lo:[0,0,1] neg_hi:[0,0,1]
	v_pk_fma_f32 v[18:19], v[18:19], v[90:91], v[210:211] op_sel_hi:[1,0,1] neg_lo:[0,0,1] neg_hi:[0,0,1]
	v_pk_fma_f32 v[16:17], v[16:17], v[90:91], v[208:209] op_sel_hi:[1,0,1] neg_lo:[0,0,1] neg_hi:[0,0,1]
	v_pk_fma_f32 v[22:23], v[22:23], v[90:91], v[216:217] op_sel_hi:[1,0,1] neg_lo:[0,0,1] neg_hi:[0,0,1]
	v_pk_fma_f32 v[20:21], v[20:21], v[90:91], v[214:215] op_sel_hi:[1,0,1] neg_lo:[0,0,1] neg_hi:[0,0,1]
	v_pk_fma_f32 v[24:25], v[24:25], v[90:91], v[218:219] op_sel_hi:[1,0,1] neg_lo:[0,0,1] neg_hi:[0,0,1]
	v_add_f32_e32 v90, v224, v225
	v_add_f32_e32 v90, v90, v222
	v_pk_mul_f32 v[228:229], v[120:121], v[120:121]
; #define LAS __attribute__((address_space(3)))
; __device__ __forceinline__ unsigned cvtpk(float lo, float hi) { f32x2 v = {lo, hi}; bf16x2_t b = __builtin_convertvector(v, bf16x2_t); return __builtin_bit_cast(unsigned, b); }
; __device__ __forceinline__ void attn_unit(unsigned char* ws, const float* sub_g, LAS unsigned char* lds, int h, int qb, float negM, float lam) {
;     ...
;         ss += __shfl_xor(ss, 32);
;         const float rs = __builtin_amdgcn_rsqf(ss * (1.0f / VD) + EPS) * (1.0f - LAM_INIT);
;         LAS unsigned char* stg = (LAS unsigned char*)xw;
; #pragma unroll
;         for (int b = 0; b < 4; ++b)
; #pragma unroll
;             for (int r4 = 0; r4 < 4; ++r4) {
;                 const int dv = 32 * b + 8 * r4 + 4 * hi;
;                 const f32x4 sg = *(const f32x4*)(sub_g + dv);
;                 u32x2 w; w.x = cvtpk(o[b][4 * r4 + 0] * rs * sg[0], o[b][4 * r4 + 1] * rs * sg[1]); w.y = cvtpk(o[b][4 * r4 + 2] * rs * sg[2], o[b][4 * r4 + 3] * rs * sg[3]);
;                 *(LAS u32x2*)(stg + r32 * 272 + dv * 2) = w;
;             }
	v_add_f32_e32 v90, v90, v223
	v_add_f32_e32 v90, v90, v228
	v_pk_mul_f32 v[226:227], v[112:113], v[112:113]
	global_load_dwordx4 v[72:75], v[132:133], off offset:64
	global_load_dwordx4 v[68:71], v[132:133], off offset:96
	v_add_f32_e32 v90, v90, v229
	v_add_f32_e32 v90, v90, v226
	v_pk_mul_f32 v[232:233], v[124:125], v[124:125]
	v_add_f32_e32 v90, v90, v227
	v_add_f32_e32 v90, v90, v232
	v_pk_mul_f32 v[230:231], v[118:119], v[118:119]
	v_add_f32_e32 v90, v90, v233
	v_add_f32_e32 v90, v90, v230
	v_pk_mul_f32 v[236:237], v[126:127], v[126:127]
	v_add_f32_e32 v90, v90, v231
	v_add_f32_e32 v90, v90, v236
	v_pk_mul_f32 v[234:235], v[122:123], v[122:123]
	v_add_f32_e32 v90, v90, v237
	v_add_f32_e32 v90, v90, v234
	v_pk_mul_f32 v[140:141], v[78:79], v[78:79]
	v_add_f32_e32 v90, v90, v235
	v_add_f32_e32 v90, v90, v140
	v_pk_mul_f32 v[142:143], v[76:77], v[76:77]
	v_add_f32_e32 v90, v90, v141
	v_add_f32_e32 v90, v90, v142
	v_pk_mul_f32 v[144:145], v[94:95], v[94:95]
	v_add_f32_e32 v90, v90, v143
	v_add_f32_e32 v90, v90, v144
	v_pk_mul_f32 v[146:147], v[92:93], v[92:93]
	v_add_f32_e32 v90, v90, v145
	v_add_f32_e32 v90, v90, v146
	v_pk_mul_f32 v[184:185], v[98:99], v[98:99]
	v_add_f32_e32 v90, v90, v147
	v_add_f32_e32 v90, v90, v184
	v_pk_mul_f32 v[186:187], v[96:97], v[96:97]
	v_add_f32_e32 v90, v90, v185
	v_add_f32_e32 v90, v90, v186
	v_pk_mul_f32 v[188:189], v[102:103], v[102:103]
	v_add_f32_e32 v90, v90, v187
	v_add_f32_e32 v90, v90, v188
	v_pk_mul_f32 v[190:191], v[100:101], v[100:101]
	v_add_f32_e32 v90, v90, v189
	v_add_f32_e32 v90, v90, v190
	v_pk_mul_f32 v[192:193], v[104:105], v[104:105]
	v_add_f32_e32 v90, v90, v191
	v_add_f32_e32 v90, v90, v192
	v_pk_mul_f32 v[194:195], v[34:35], v[34:35]
	v_add_f32_e32 v90, v90, v193
	v_add_f32_e32 v90, v90, v194
	v_pk_mul_f32 v[196:197], v[36:37], v[36:37]
	v_add_f32_e32 v90, v90, v195
	v_add_f32_e32 v90, v90, v196
	v_pk_mul_f32 v[198:199], v[38:39], v[38:39]
	v_add_f32_e32 v90, v90, v197
	v_add_f32_e32 v90, v90, v198
	v_pk_mul_f32 v[200:201], v[40:41], v[40:41]
	v_add_f32_e32 v90, v90, v199
	v_add_f32_e32 v90, v90, v200
	v_pk_mul_f32 v[202:203], v[42:43], v[42:43]
	v_add_f32_e32 v90, v90, v201
	v_add_f32_e32 v90, v90, v202
	v_pk_mul_f32 v[204:205], v[44:45], v[44:45]
	v_add_f32_e32 v90, v90, v203
	v_add_f32_e32 v90, v90, v204
	v_pk_mul_f32 v[206:207], v[46:47], v[46:47]
	v_add_f32_e32 v90, v90, v205
	v_add_f32_e32 v90, v90, v206
	v_pk_mul_f32 v[208:209], v[16:17], v[16:17]
	v_add_f32_e32 v90, v90, v207
	v_add_f32_e32 v90, v90, v208
	v_pk_mul_f32 v[210:211], v[18:19], v[18:19]
	v_add_f32_e32 v90, v90, v209
	v_add_f32_e32 v90, v90, v210
	v_pk_mul_f32 v[214:215], v[20:21], v[20:21]
	v_add_f32_e32 v90, v90, v211
	v_add_f32_e32 v90, v90, v214
	v_pk_mul_f32 v[216:217], v[22:23], v[22:23]
	v_add_f32_e32 v90, v90, v215
	v_add_f32_e32 v90, v90, v216
	v_pk_mul_f32 v[218:219], v[24:25], v[24:25]
	v_add_f32_e32 v90, v90, v217
	v_add_f32_e32 v90, v90, v218
	v_add_f32_e32 v90, v90, v219
	v_add_f32_e32 v90, v90, v108
	v_pk_mul_f32 v[110:111], v[84:85], v[84:85]
	v_add_f32_e32 v90, v90, v109
	v_add_f32_e32 v90, v90, v110
	v_pk_mul_f32 v[116:117], v[88:89], v[88:89]
	v_add_f32_e32 v90, v90, v111
	v_add_f32_e32 v90, v90, v116
	v_add_f32_e32 v90, v90, v117
	ds_bpermute_b32 v116, v212, v90
	global_load_dwordx4 v[48:51], v[132:133], off offset:128
	global_load_dwordx4 v[26:29], v[132:133], off offset:160
	global_load_dwordx4 v[56:59], v[132:133], off offset:192
	global_load_dwordx4 v[52:55], v[132:133], off offset:224
	v_add_u32_e32 v130, v91, v128
	global_load_dwordx4 v[60:63], v[132:133], off offset:256
	global_load_dwordx4 v[30:33], v[132:133], off offset:288
	s_waitcnt lgkmcnt(0)
	v_add_f32_e32 v90, v90, v116
	v_fmamk_f32 v90, v90, 0x3c000000, v182
	v_rsq_f32_e32 v90, v90
	global_load_dwordx4 v[108:111], v[132:133], off offset:320
	global_load_dwordx4 v[140:143], v[132:133], off offset:352
	global_load_dwordx4 v[144:147], v[132:133], off offset:384
	global_load_dwordx4 v[184:187], v[132:133], off offset:416
	v_add_u32_e32 v183, v91, v156
	v_mul_f32_e32 v90, 0x3f4ccccd, v90
	v_pk_mul_f32 v[114:115], v[114:115], v[90:91] op_sel_hi:[1,0]
	v_pk_mul_f32 v[106:107], v[106:107], v[90:91] op_sel_hi:[1,0]
	s_waitcnt vmcnt(13)
	v_pk_mul_f32 v[80:81], v[80:81], v[114:115]
	v_pk_mul_f32 v[82:83], v[82:83], v[106:107]
	v_cvt_pk_bf16_f32 v80, v80, v81
	v_cvt_pk_bf16_f32 v81, v82, v83
	ds_write_b64 v130, v[80:81]
	v_pk_mul_f32 v[80:81], v[120:121], v[90:91] op_sel_hi:[1,0]
	v_add_u32_e32 v213, v91, v157
	s_waitcnt vmcnt(12)
	v_pk_mul_f32 v[64:65], v[64:65], v[80:81]
	v_pk_mul_f32 v[80:81], v[112:113], v[90:91] op_sel_hi:[1,0]
	v_cvt_pk_bf16_f32 v64, v64, v65
	v_pk_mul_f32 v[66:67], v[66:67], v[80:81]
	global_load_dwordx4 v[188:191], v[132:133], off offset:448
	v_cvt_pk_bf16_f32 v65, v66, v67
	ds_write_b64 v183, v[64:65]
	v_pk_mul_f32 v[64:65], v[124:125], v[90:91] op_sel_hi:[1,0]
	v_pk_mul_f32 v[66:67], v[118:119], v[90:91] op_sel_hi:[1,0]
	s_waitcnt vmcnt(12)
	v_pk_mul_f32 v[64:65], v[72:73], v[64:65]
	v_pk_mul_f32 v[66:67], v[74:75], v[66:67]
	v_cvt_pk_bf16_f32 v64, v64, v65
	v_cvt_pk_bf16_f32 v65, v66, v67
	ds_write_b64 v213, v[64:65]
	v_pk_mul_f32 v[64:65], v[126:127], v[90:91] op_sel_hi:[1,0]
	v_pk_mul_f32 v[66:67], v[122:123], v[90:91] op_sel_hi:[1,0]
	s_waitcnt vmcnt(11)
; #define LAS __attribute__((address_space(3)))
; __device__ __forceinline__ unsigned cvtpk(float lo, float hi) { f32x2 v = {lo, hi}; bf16x2_t b = __builtin_convertvector(v, bf16x2_t); return __builtin_bit_cast(unsigned, b); }
; __device__ __forceinline__ void attn_unit(unsigned char* ws, const float* sub_g, LAS unsigned char* lds, int h, int qb, float negM, float lam) {
;     ...
;                 const int dv = 32 * b + 8 * r4 + 4 * hi;
;                 const f32x4 sg = *(const f32x4*)(sub_g + dv);
;                 u32x2 w; w.x = cvtpk(o[b][4 * r4 + 0] * rs * sg[0], o[b][4 * r4 + 1] * rs * sg[1]); w.y = cvtpk(o[b][4 * r4 + 2] * rs * sg[2], o[b][4 * r4 + 3] * rs * sg[3]);
;                 *(LAS u32x2*)(stg + r32 * 272 + dv * 2) = w;
;             }
;         asm volatile("s_waitcnt lgkmcnt(0)" ::: "memory");
;         const bf16_t* GA = (const bf16_t*)(ws + WS_GA); bf16_t* MIX = (bf16_t*)(ws + WS_MIX);
;         u32x4 gvs[8];
; #pragma unroll
;         for (int i = 0; i < 8; ++i) gvs[i] = *(const u32x4*)(GA + (size_t)(qrow0 + (lane >> 4) + 4 * i) * 1024 + h * 128 + (lane & 15) * 8);
; #pragma unroll
;         for (int i = 0; i < 8; ++i) {
;             const int q = (lane >> 4) + 4 * i, ch = lane & 15;
;             const u32x4 ov = *(const LAS u32x4*)(stg + q * 272 + ch * 16);
	v_pk_mul_f32 v[64:65], v[68:69], v[64:65]
	v_pk_mul_f32 v[66:67], v[70:71], v[66:67]
	v_add_u32_e32 v238, v91, v158
	v_cvt_pk_bf16_f32 v64, v64, v65
	v_cvt_pk_bf16_f32 v65, v66, v67
	ds_write_b64 v238, v[64:65]
	global_load_dwordx4 v[64:67], v[132:133], off offset:480
	v_pk_mul_f32 v[68:69], v[78:79], v[90:91] op_sel_hi:[1,0]
	v_add_u32_e32 v239, v91, v159
	v_add_u32_e32 v240, v91, v160
	v_add_u32_e32 v241, v91, v161
	v_add_u32_e32 v242, v91, v162
	v_pk_mul_f32 v[16:17], v[16:17], v[90:91] op_sel_hi:[1,0]
	v_pk_mul_f32 v[18:19], v[18:19], v[90:91] op_sel_hi:[1,0]
	v_add_u32_e32 v243, v91, v163
	v_add_u32_e32 v192, v91, v167
	v_add_u32_e32 v244, v91, v164
	v_add_u32_e32 v116, v91, v168
	v_add_u32_e32 v245, v91, v165
	v_add_u32_e32 v117, v91, v166
	s_waitcnt vmcnt(11)
	v_pk_mul_f32 v[48:49], v[68:69], v[48:49]
	v_pk_mul_f32 v[68:69], v[76:77], v[90:91] op_sel_hi:[1,0]
	v_cvt_pk_bf16_f32 v48, v48, v49
	v_pk_mul_f32 v[50:51], v[68:69], v[50:51]
	s_waitcnt vmcnt(3)
	v_pk_mul_f32 v[16:17], v[16:17], v[144:145]
	v_cvt_pk_bf16_f32 v49, v50, v51
	ds_write_b64 v239, v[48:49]
	v_pk_mul_f32 v[48:49], v[94:95], v[90:91] op_sel_hi:[1,0]
	v_pk_mul_f32 v[18:19], v[18:19], v[146:147]
	v_pk_mul_f32 v[26:27], v[48:49], v[26:27]
	v_pk_mul_f32 v[48:49], v[92:93], v[90:91] op_sel_hi:[1,0]
	v_cvt_pk_bf16_f32 v26, v26, v27
	v_pk_mul_f32 v[28:29], v[48:49], v[28:29]
	v_cvt_pk_bf16_f32 v16, v16, v17
	v_cvt_pk_bf16_f32 v27, v28, v29
	ds_write_b64 v240, v[26:27]
	v_pk_mul_f32 v[26:27], v[98:99], v[90:91] op_sel_hi:[1,0]
	v_pk_mul_f32 v[28:29], v[96:97], v[90:91] op_sel_hi:[1,0]
	v_pk_mul_f32 v[26:27], v[26:27], v[56:57]
	v_pk_mul_f32 v[28:29], v[28:29], v[58:59]
	v_cvt_pk_bf16_f32 v26, v26, v27
	v_cvt_pk_bf16_f32 v27, v28, v29
	ds_write_b64 v241, v[26:27]
	v_pk_mul_f32 v[26:27], v[102:103], v[90:91] op_sel_hi:[1,0]
	v_pk_mul_f32 v[28:29], v[100:101], v[90:91] op_sel_hi:[1,0]
	v_pk_mul_f32 v[26:27], v[26:27], v[52:53]
	v_pk_mul_f32 v[28:29], v[28:29], v[54:55]
	v_cvt_pk_bf16_f32 v26, v26, v27
	v_cvt_pk_bf16_f32 v27, v28, v29
	ds_write_b64 v242, v[26:27]
	v_pk_mul_f32 v[26:27], v[104:105], v[90:91] op_sel_hi:[1,0]
	v_pk_mul_f32 v[28:29], v[34:35], v[90:91] op_sel_hi:[1,0]
	v_pk_mul_f32 v[26:27], v[26:27], v[60:61]
	v_pk_mul_f32 v[28:29], v[28:29], v[62:63]
	v_cvt_pk_bf16_f32 v26, v26, v27
	v_cvt_pk_bf16_f32 v27, v28, v29
	v_cvt_pk_bf16_f32 v17, v18, v19
	ds_write_b64 v243, v[26:27]
	v_pk_mul_f32 v[26:27], v[36:37], v[90:91] op_sel_hi:[1,0]
	v_pk_mul_f32 v[28:29], v[38:39], v[90:91] op_sel_hi:[1,0]
	ds_write_b64 v192, v[16:17]
	v_pk_mul_f32 v[16:17], v[20:21], v[90:91] op_sel_hi:[1,0]
	v_pk_mul_f32 v[18:19], v[22:23], v[90:91] op_sel_hi:[1,0]
	v_pk_mul_f32 v[26:27], v[26:27], v[30:31]
	v_pk_mul_f32 v[28:29], v[28:29], v[32:33]
	s_waitcnt vmcnt(2)
	v_pk_mul_f32 v[16:17], v[16:17], v[184:185]
	v_pk_mul_f32 v[18:19], v[18:19], v[186:187]
	v_cvt_pk_bf16_f32 v26, v26, v27
	v_cvt_pk_bf16_f32 v27, v28, v29
	v_cvt_pk_bf16_f32 v16, v16, v17
	v_cvt_pk_bf16_f32 v17, v18, v19
	ds_write_b64 v244, v[26:27]
	v_pk_mul_f32 v[26:27], v[40:41], v[90:91] op_sel_hi:[1,0]
	v_pk_mul_f32 v[28:29], v[42:43], v[90:91] op_sel_hi:[1,0]
	ds_write_b64 v116, v[16:17]
	v_pk_mul_f32 v[16:17], v[24:25], v[90:91] op_sel_hi:[1,0]
	v_pk_mul_f32 v[18:19], v[86:87], v[90:91] op_sel_hi:[1,0]
	v_pk_mul_f32 v[26:27], v[26:27], v[108:109]
	v_pk_mul_f32 v[28:29], v[28:29], v[110:111]
	s_waitcnt vmcnt(1)
	v_pk_mul_f32 v[16:17], v[16:17], v[188:189]
	v_pk_mul_f32 v[18:19], v[18:19], v[190:191]
	v_cvt_pk_bf16_f32 v26, v26, v27
	v_cvt_pk_bf16_f32 v27, v28, v29
	v_cvt_pk_bf16_f32 v16, v16, v17
	v_cvt_pk_bf16_f32 v17, v18, v19
	v_add_u32_e32 v18, v91, v169
	ds_write_b64 v245, v[26:27]
	v_pk_mul_f32 v[26:27], v[44:45], v[90:91] op_sel_hi:[1,0]
	v_pk_mul_f32 v[28:29], v[46:47], v[90:91] op_sel_hi:[1,0]
	ds_write_b64 v18, v[16:17]
	v_pk_mul_f32 v[16:17], v[84:85], v[90:91] op_sel_hi:[1,0]
	v_pk_mul_f32 v[18:19], v[88:89], v[90:91] op_sel_hi:[1,0]
	v_pk_mul_f32 v[26:27], v[26:27], v[140:141]
	v_pk_mul_f32 v[28:29], v[28:29], v[142:143]
	s_waitcnt vmcnt(0)
	v_pk_mul_f32 v[16:17], v[16:17], v[64:65]
	v_pk_mul_f32 v[18:19], v[18:19], v[66:67]
	v_or_b32_e32 v58, s21, v150
	v_cvt_pk_bf16_f32 v26, v26, v27
	v_cvt_pk_bf16_f32 v27, v28, v29
	v_cvt_pk_bf16_f32 v16, v16, v17
	v_cvt_pk_bf16_f32 v17, v18, v19
	v_add_u32_e32 v18, v91, v170
	v_ashrrev_i32_e32 v59, 31, v58
	ds_write_b64 v117, v[26:27]
	ds_write_b64 v18, v[16:17]
	v_lshl_add_u64 v[16:17], v[134:135], 0, s[8:9]
	v_lshlrev_b64 v[18:19], 11, v[58:59]
	s_waitcnt lgkmcnt(0)
	v_lshl_add_u64 v[18:19], v[16:17], 0, v[18:19]
	global_load_dwordx4 v[38:41], v[18:19], off
	v_or_b32_e32 v18, 4, v58
	v_ashrrev_i32_e32 v19, 31, v18
	v_lshlrev_b64 v[18:19], 11, v[18:19]
	v_lshl_add_u64 v[18:19], v[16:17], 0, v[18:19]
	global_load_dwordx4 v[42:45], v[18:19], off
	v_or_b32_e32 v18, 8, v58
	v_ashrrev_i32_e32 v19, 31, v18
	v_or_b32_e32 v20, 12, v58
	v_lshlrev_b64 v[18:19], 11, v[18:19]
	v_ashrrev_i32_e32 v21, 31, v20
	v_lshl_add_u64 v[18:19], v[16:17], 0, v[18:19]
	v_lshlrev_b64 v[20:21], 11, v[20:21]
	v_lshl_add_u64 v[20:21], v[16:17], 0, v[20:21]
	global_load_dwordx4 v[46:49], v[18:19], off
	global_load_dwordx4 v[32:35], v[20:21], off
	v_or_b32_e32 v18, 16, v58
	v_ashrrev_i32_e32 v19, 31, v18
	v_or_b32_e32 v20, 20, v58
	v_lshlrev_b64 v[18:19], 11, v[18:19]
	v_ashrrev_i32_e32 v21, 31, v20
	v_lshl_add_u64 v[18:19], v[16:17], 0, v[18:19]
	v_lshlrev_b64 v[20:21], 11, v[20:21]
	v_lshl_add_u64 v[20:21], v[16:17], 0, v[20:21]
	global_load_dwordx4 v[28:31], v[18:19], off
	global_load_dwordx4 v[24:27], v[20:21], off
	v_or_b32_e32 v18, 24, v58
	v_ashrrev_i32_e32 v19, 31, v18
	v_lshlrev_b64 v[18:19], 11, v[18:19]
	v_lshl_add_u64 v[36:37], v[16:17], 0, v[18:19]
	v_or_b32_e32 v18, 28, v58
	v_ashrrev_i32_e32 v19, 31, v18
	v_lshlrev_b64 v[18:19], 11, v[18:19]
	v_add3_u32 v64, s29, v136, v137
	v_lshl_add_u64 v[54:55], v[16:17], 0, v[18:19]
	ds_read_b128 v[50:53], v64
	global_load_dwordx4 v[20:23], v[36:37], off
	global_load_dwordx4 v[16:19], v[54:55], off
	ds_read_b128 v[54:57], v64 offset:1088
	v_lshl_add_u64 v[36:37], v[138:139], 0, s[8:9]
	s_waitcnt lgkmcnt(1)
; #define LAS __attribute__((address_space(3)))
; __device__ __forceinline__ unsigned cvtpk(float lo, float hi) { f32x2 v = {lo, hi}; bf16x2_t b = __builtin_convertvector(v, bf16x2_t); return __builtin_bit_cast(unsigned, b); }
; __device__ __forceinline__ void attn_unit(unsigned char* ws, const float* sub_g, LAS unsigned char* lds, int h, int qb, float negM, float lam) {
;     ...
;         for (int i = 0; i < 8; ++i) {
;             const int q = (lane >> 4) + 4 * i, ch = lane & 15;
;             const u32x4 ov = *(const LAS u32x4*)(stg + q * 272 + ch * 16);
;             const size_t tok = (size_t)(qrow0 + q);
;             const u32x4 gv = gvs[i];
;             u32x4 w;
;             w.x = cvtpk(bf_lo(ov.x) * bf_lo(gv.x), bf_hi(ov.x) * bf_hi(gv.x)); w.y = cvtpk(bf_lo(ov.y) * bf_lo(gv.y), bf_hi(ov.y) * bf_hi(gv.y));
;             w.z = cvtpk(bf_lo(ov.z) * bf_lo(gv.z), bf_hi(ov.z) * bf_hi(gv.z)); w.w = cvtpk(bf_lo(ov.w) * bf_lo(gv.w), bf_hi(ov.w) * bf_hi(gv.w));
;             *(u32x4*)(MIX + tok * DM + h * 128 + ch * 8) = w;
	v_lshlrev_b32_e32 v60, 16, v50
	v_and_b32_e32 v61, 0xffff0000, v50
	v_lshlrev_b32_e32 v50, 16, v51
	v_and_b32_e32 v51, 0xffff0000, v51
	s_waitcnt vmcnt(7)
	v_lshlrev_b32_e32 v62, 16, v38
	v_and_b32_e32 v63, 0xffff0000, v38
	v_pk_mul_f32 v[60:61], v[62:63], v[60:61]
	s_nop 0
	v_cvt_pk_bf16_f32 v38, v60, v61
	v_lshlrev_b32_e32 v60, 16, v39
	v_and_b32_e32 v61, 0xffff0000, v39
	v_pk_mul_f32 v[50:51], v[60:61], v[50:51]
	v_lshlrev_b32_e32 v60, 16, v40
	v_cvt_pk_bf16_f32 v39, v50, v51
	v_lshlrev_b32_e32 v50, 16, v52
	v_and_b32_e32 v51, 0xffff0000, v52
	v_and_b32_e32 v61, 0xffff0000, v40
	v_pk_mul_f32 v[50:51], v[60:61], v[50:51]
	v_lshlrev_b32_e32 v52, 16, v41
	v_cvt_pk_bf16_f32 v40, v50, v51
	v_lshlrev_b32_e32 v50, 16, v53
	v_and_b32_e32 v51, 0xffff0000, v53
	v_and_b32_e32 v53, 0xffff0000, v41
	v_pk_mul_f32 v[50:51], v[52:53], v[50:51]
	s_nop 0
	v_cvt_pk_bf16_f32 v41, v50, v51
	v_lshlrev_b64 v[50:51], 12, v[58:59]
	v_lshl_add_u64 v[50:51], v[36:37], 0, v[50:51]
	global_store_dwordx4 v[50:51], v[38:41], off sc1
	v_or_b32_e32 v50, s21, v171
	v_ashrrev_i32_e32 v51, 31, v50
	s_waitcnt lgkmcnt(0)
	v_lshlrev_b32_e32 v38, 16, v54
	v_and_b32_e32 v39, 0xffff0000, v54
	s_waitcnt vmcnt(7)
	v_lshlrev_b32_e32 v40, 16, v42
	v_and_b32_e32 v41, 0xffff0000, v42
	v_pk_mul_f32 v[38:39], v[40:41], v[38:39]
	v_lshlrev_b32_e32 v40, 16, v55
	v_and_b32_e32 v41, 0xffff0000, v55
	v_lshlrev_b32_e32 v42, 16, v43
	v_and_b32_e32 v43, 0xffff0000, v43
	v_pk_mul_f32 v[40:41], v[42:43], v[40:41]
	v_cvt_pk_bf16_f32 v38, v38, v39
	v_cvt_pk_bf16_f32 v39, v40, v41
	v_lshlrev_b32_e32 v40, 16, v56
	v_and_b32_e32 v41, 0xffff0000, v56
	v_lshlrev_b32_e32 v42, 16, v44
	v_and_b32_e32 v43, 0xffff0000, v44
	v_pk_mul_f32 v[40:41], v[42:43], v[40:41]
	v_lshlrev_b32_e32 v42, 16, v57
	v_and_b32_e32 v43, 0xffff0000, v57
	v_lshlrev_b32_e32 v44, 16, v45
	v_and_b32_e32 v45, 0xffff0000, v45
	v_pk_mul_f32 v[42:43], v[44:45], v[42:43]
	v_cvt_pk_bf16_f32 v40, v40, v41
	v_cvt_pk_bf16_f32 v41, v42, v43
	v_lshlrev_b64 v[42:43], 12, v[50:51]
	v_lshl_add_u64 v[50:51], v[36:37], 0, v[42:43]
	ds_read_b128 v[42:45], v64 offset:2176
	global_store_dwordx4 v[50:51], v[38:41], off sc1
	ds_read_b128 v[38:41], v64 offset:3264
	s_waitcnt vmcnt(7)
	v_lshlrev_b32_e32 v54, 16, v46
	v_and_b32_e32 v55, 0xffff0000, v46
	s_waitcnt lgkmcnt(1)
	v_lshlrev_b32_e32 v52, 16, v42
	v_and_b32_e32 v53, 0xffff0000, v42
	v_pk_mul_f32 v[52:53], v[54:55], v[52:53]
	v_lshlrev_b32_e32 v46, 16, v47
	v_cvt_pk_bf16_f32 v42, v52, v53
	v_lshlrev_b32_e32 v52, 16, v43
	v_and_b32_e32 v53, 0xffff0000, v43
	v_and_b32_e32 v47, 0xffff0000, v47
	v_pk_mul_f32 v[46:47], v[46:47], v[52:53]
	v_lshlrev_b32_e32 v52, 16, v48
	v_cvt_pk_bf16_f32 v43, v46, v47
	v_lshlrev_b32_e32 v46, 16, v44
	v_and_b32_e32 v47, 0xffff0000, v44
	v_and_b32_e32 v53, 0xffff0000, v48
	v_pk_mul_f32 v[46:47], v[52:53], v[46:47]
	v_or_b32_e32 v50, s21, v172
	v_cvt_pk_bf16_f32 v44, v46, v47
	v_lshlrev_b32_e32 v46, 16, v45
	v_and_b32_e32 v47, 0xffff0000, v45
	v_lshlrev_b32_e32 v48, 16, v49
	v_and_b32_e32 v49, 0xffff0000, v49
	v_ashrrev_i32_e32 v51, 31, v50
	v_pk_mul_f32 v[46:47], v[48:49], v[46:47]
	s_nop 0
	v_cvt_pk_bf16_f32 v45, v46, v47
	v_lshlrev_b64 v[46:47], 12, v[50:51]
	v_lshl_add_u64 v[46:47], v[36:37], 0, v[46:47]
	global_store_dwordx4 v[46:47], v[42:45], off sc1
	s_waitcnt vmcnt(7)
	v_lshlrev_b32_e32 v46, 16, v32
	v_and_b32_e32 v47, 0xffff0000, v32
	s_waitcnt lgkmcnt(0)
	v_lshlrev_b32_e32 v44, 16, v38
	v_and_b32_e32 v45, 0xffff0000, v38
	v_pk_mul_f32 v[44:45], v[46:47], v[44:45]
	v_lshlrev_b32_e32 v38, 16, v39
	v_cvt_pk_bf16_f32 v32, v44, v45
	v_and_b32_e32 v39, 0xffff0000, v39
	v_lshlrev_b32_e32 v44, 16, v33
	v_and_b32_e32 v45, 0xffff0000, v33
	v_pk_mul_f32 v[38:39], v[44:45], v[38:39]
	v_lshlrev_b32_e32 v44, 16, v34
	v_cvt_pk_bf16_f32 v33, v38, v39
	v_lshlrev_b32_e32 v38, 16, v40
	v_and_b32_e32 v39, 0xffff0000, v40
	v_and_b32_e32 v45, 0xffff0000, v34
	v_pk_mul_f32 v[38:39], v[44:45], v[38:39]
	v_or_b32_e32 v42, s21, v173
	v_cvt_pk_bf16_f32 v34, v38, v39
	v_lshlrev_b32_e32 v38, 16, v41
	v_and_b32_e32 v39, 0xffff0000, v41
	v_lshlrev_b32_e32 v40, 16, v35
	v_and_b32_e32 v41, 0xffff0000, v35
	v_ashrrev_i32_e32 v43, 31, v42
	v_pk_mul_f32 v[38:39], v[40:41], v[38:39]
	s_waitcnt vmcnt(6)
	v_lshlrev_b32_e32 v46, 16, v28
	v_cvt_pk_bf16_f32 v35, v38, v39
	v_lshlrev_b64 v[38:39], 12, v[42:43]
	v_lshl_add_u64 v[42:43], v[36:37], 0, v[38:39]
	ds_read_b128 v[38:41], v64 offset:4352
	global_store_dwordx4 v[42:43], v[32:35], off sc1
	ds_read_b128 v[32:35], v64 offset:5440
	v_and_b32_e32 v47, 0xffff0000, v28
	v_or_b32_e32 v42, s21, v174
	s_waitcnt lgkmcnt(1)
; #define LAS __attribute__((address_space(3)))
; __device__ __forceinline__ unsigned xb_ld(unsigned* p)              { return __hip_atomic_load(p, __ATOMIC_RELAXED, __HIP_MEMORY_SCOPE_AGENT); }
; __device__ __forceinline__ void attn_unit(unsigned char* ws, const float* sub_g, LAS unsigned char* lds, int h, int qb, float negM, float lam) {
;     ...
;         for (int i = 0; i < 8; ++i) {
;             const int q = (lane >> 4) + 4 * i, ch = lane & 15;
;             const u32x4 ov = *(const LAS u32x4*)(stg + q * 272 + ch * 16);
;             const size_t tok = (size_t)(qrow0 + q);
;             const u32x4 gv = gvs[i];
;             u32x4 w;
;             w.x = cvtpk(bf_lo(ov.x) * bf_lo(gv.x), bf_hi(ov.x) * bf_hi(gv.x)); w.y = cvtpk(bf_lo(ov.y) * bf_lo(gv.y), bf_hi(ov.y) * bf_hi(gv.y));
;             w.z = cvtpk(bf_lo(ov.z) * bf_lo(gv.z), bf_hi(ov.z) * bf_hi(gv.z)); w.w = cvtpk(bf_lo(ov.w) * bf_lo(gv.w), bf_hi(ov.w) * bf_hi(gv.w));
;             *(u32x4*)(MIX + tok * DM + h * 128 + ch * 8) = w;
;         }
; __device__ __forceinline__ void xcd_barrier(const XcdBarrier& b) {
;     asm volatile("s_waitcnt vmcnt(0)" ::: "memory");
;     __syncthreads();
;     if (threadIdx.x == 0) {
;         unsigned* bar = b.bar;
;         __builtin_amdgcn_s_waitcnt(0);
;         unsigned nloc = b.st[0], nx = b.st[1];
;         if (nloc == 0u) { unsigned uni; xcd_barrier_complete(bar, b.x, nloc, nx, uni); b.st[0] = nloc; b.st[1] = nx; b.st[2] = uni; }
;         const unsigned old = xb_add(&bar[XB_XSUB(b.x)], 1u);
;         const unsigned gen = old / nloc;
;         if (old + 1u == (gen + 1u) * nloc) {
;             __builtin_amdgcn_fence(__ATOMIC_RELEASE, "agent");
;             asm volatile("s_waitcnt vmcnt(0)" ::: "memory");
;             const unsigned og = xb_add(&bar[XB_TOP], 1u);
;             const unsigned tg = og / nx;
;             if (og + 1u == (tg + 1u) * nx) xb_add(&bar[XB_TOPGEN], 1u);
;             else XB_SPIN(xb_ld(&bar[XB_TOPGEN]) == tg, bar);
;             __builtin_amdgcn_fence(__ATOMIC_ACQUIRE, "agent");
;             xb_add(&bar[XB_XGEN(b.x)], 1u);
;             asm volatile("s_waitcnt vmcnt(0)" ::: "memory");
;         } else {
;             XB_SPIN(xb_ld(&bar[XB_XGEN(b.x)]) == gen, bar);
;             __builtin_amdgcn_fence(__ATOMIC_ACQUIRE, "agent");
;             asm volatile("s_waitcnt vmcnt(0)" ::: "memory");
;         }
;     }
;     __syncthreads();
; }
	v_lshlrev_b32_e32 v44, 16, v38
	v_and_b32_e32 v45, 0xffff0000, v38
	v_pk_mul_f32 v[44:45], v[46:47], v[44:45]
	v_lshlrev_b32_e32 v38, 16, v39
	v_cvt_pk_bf16_f32 v28, v44, v45
	v_and_b32_e32 v39, 0xffff0000, v39
	v_lshlrev_b32_e32 v44, 16, v29
	v_and_b32_e32 v45, 0xffff0000, v29
	v_pk_mul_f32 v[38:39], v[44:45], v[38:39]
	v_lshlrev_b32_e32 v44, 16, v30
	v_cvt_pk_bf16_f32 v29, v38, v39
	v_lshlrev_b32_e32 v38, 16, v40
	v_and_b32_e32 v39, 0xffff0000, v40
	v_and_b32_e32 v45, 0xffff0000, v30
	v_pk_mul_f32 v[38:39], v[44:45], v[38:39]
	v_lshlrev_b32_e32 v40, 16, v31
	v_cvt_pk_bf16_f32 v30, v38, v39
	v_lshlrev_b32_e32 v38, 16, v41
	v_and_b32_e32 v39, 0xffff0000, v41
	v_and_b32_e32 v41, 0xffff0000, v31
	v_ashrrev_i32_e32 v43, 31, v42
	v_pk_mul_f32 v[38:39], v[40:41], v[38:39]
	s_nop 0
	v_cvt_pk_bf16_f32 v31, v38, v39
	v_lshlrev_b64 v[38:39], 12, v[42:43]
	v_lshl_add_u64 v[38:39], v[36:37], 0, v[38:39]
	global_store_dwordx4 v[38:39], v[28:31], off sc1
	s_waitcnt vmcnt(7)
	v_lshlrev_b32_e32 v38, 16, v24
	v_and_b32_e32 v39, 0xffff0000, v24
	s_waitcnt lgkmcnt(0)
	v_lshlrev_b32_e32 v30, 16, v32
	v_and_b32_e32 v31, 0xffff0000, v32
	v_pk_mul_f32 v[30:31], v[38:39], v[30:31]
	v_lshlrev_b32_e32 v32, 16, v25
	v_cvt_pk_bf16_f32 v24, v30, v31
	v_lshlrev_b32_e32 v30, 16, v33
	v_and_b32_e32 v31, 0xffff0000, v33
	v_and_b32_e32 v33, 0xffff0000, v25
	v_pk_mul_f32 v[30:31], v[32:33], v[30:31]
	v_lshlrev_b32_e32 v32, 16, v26
	v_cvt_pk_bf16_f32 v25, v30, v31
	v_lshlrev_b32_e32 v30, 16, v34
	v_and_b32_e32 v31, 0xffff0000, v34
	v_and_b32_e32 v33, 0xffff0000, v26
	v_or_b32_e32 v28, s21, v175
	v_pk_mul_f32 v[30:31], v[32:33], v[30:31]
	v_ashrrev_i32_e32 v29, 31, v28
	v_cvt_pk_bf16_f32 v26, v30, v31
	v_lshlrev_b32_e32 v30, 16, v35
	v_and_b32_e32 v31, 0xffff0000, v35
	v_lshlrev_b32_e32 v32, 16, v27
	v_and_b32_e32 v33, 0xffff0000, v27
	v_pk_mul_f32 v[30:31], v[32:33], v[30:31]
	v_lshlrev_b64 v[28:29], 12, v[28:29]
	v_cvt_pk_bf16_f32 v27, v30, v31
	v_lshl_add_u64 v[32:33], v[36:37], 0, v[28:29]
	ds_read_b128 v[28:31], v64 offset:6528
	global_store_dwordx4 v[32:33], v[24:27], off sc1
	ds_read_b128 v[24:27], v64 offset:7616
	s_waitcnt vmcnt(7)
	v_lshlrev_b32_e32 v38, 16, v20
	v_and_b32_e32 v39, 0xffff0000, v20
	s_waitcnt lgkmcnt(1)
	v_lshlrev_b32_e32 v34, 16, v28
	v_and_b32_e32 v35, 0xffff0000, v28
	v_pk_mul_f32 v[34:35], v[38:39], v[34:35]
	v_lshlrev_b32_e32 v28, 16, v29
	v_cvt_pk_bf16_f32 v20, v34, v35
	v_and_b32_e32 v29, 0xffff0000, v29
	v_lshlrev_b32_e32 v34, 16, v21
	v_and_b32_e32 v35, 0xffff0000, v21
	v_pk_mul_f32 v[28:29], v[34:35], v[28:29]
	v_lshlrev_b32_e32 v34, 16, v22
	v_cvt_pk_bf16_f32 v21, v28, v29
	v_lshlrev_b32_e32 v28, 16, v30
	v_and_b32_e32 v29, 0xffff0000, v30
	v_and_b32_e32 v35, 0xffff0000, v22
	v_pk_mul_f32 v[28:29], v[34:35], v[28:29]
	v_or_b32_e32 v32, s21, v176
	v_cvt_pk_bf16_f32 v22, v28, v29
	v_lshlrev_b32_e32 v28, 16, v31
	v_and_b32_e32 v29, 0xffff0000, v31
	v_lshlrev_b32_e32 v30, 16, v23
	v_and_b32_e32 v31, 0xffff0000, v23
	v_ashrrev_i32_e32 v33, 31, v32
	v_pk_mul_f32 v[28:29], v[30:31], v[28:29]
	s_nop 0
	v_cvt_pk_bf16_f32 v23, v28, v29
	v_lshlrev_b64 v[28:29], 12, v[32:33]
	v_lshl_add_u64 v[28:29], v[36:37], 0, v[28:29]
	global_store_dwordx4 v[28:29], v[20:23], off sc1
	s_waitcnt vmcnt(7)
	v_lshlrev_b32_e32 v28, 16, v16
	v_and_b32_e32 v29, 0xffff0000, v16
	s_waitcnt lgkmcnt(0)
	v_lshlrev_b32_e32 v22, 16, v24
	v_and_b32_e32 v23, 0xffff0000, v24
	v_pk_mul_f32 v[22:23], v[28:29], v[22:23]
	v_lshlrev_b32_e32 v24, 16, v17
	v_cvt_pk_bf16_f32 v16, v22, v23
	v_lshlrev_b32_e32 v22, 16, v25
	v_and_b32_e32 v23, 0xffff0000, v25
	v_and_b32_e32 v25, 0xffff0000, v17
	v_pk_mul_f32 v[22:23], v[24:25], v[22:23]
	v_lshlrev_b32_e32 v24, 16, v18
	v_cvt_pk_bf16_f32 v17, v22, v23
	v_lshlrev_b32_e32 v22, 16, v26
	v_and_b32_e32 v23, 0xffff0000, v26
	v_and_b32_e32 v25, 0xffff0000, v18
	v_or_b32_e32 v20, s21, v177
	v_pk_mul_f32 v[22:23], v[24:25], v[22:23]
	v_ashrrev_i32_e32 v21, 31, v20
	v_cvt_pk_bf16_f32 v18, v22, v23
	v_lshlrev_b32_e32 v22, 16, v27
	v_and_b32_e32 v23, 0xffff0000, v27
	v_lshlrev_b32_e32 v24, 16, v19
	v_and_b32_e32 v25, 0xffff0000, v19
	v_pk_mul_f32 v[22:23], v[24:25], v[22:23]
	v_lshlrev_b64 v[20:21], 12, v[20:21]
	v_cvt_pk_bf16_f32 v19, v22, v23
	v_lshl_add_u64 v[20:21], v[36:37], 0, v[20:21]
	global_store_dwordx4 v[20:21], v[16:19], off sc1
	s_branch .LBB0_829
.LBB0_838:
	s_load_dwordx2 s[34:35], s[0:1], 0xb0
	s_waitcnt lgkmcnt(0)
	s_cmp_gt_i32 s35, 4
	s_cbranch_scc0 .LBB0_891
	s_waitcnt vmcnt(0)
	s_barrier
	s_mov_b64 s[20:21], exec
	v_readlane_b32 s4, v246, 3
	v_readlane_b32 s5, v246, 4
	s_and_b64 s[4:5], s[20:21], s[4:5]
	s_mov_b64 exec, s[4:5]
	s_cbranch_execz .Lb4_join
	v_readlane_b32 s3, v246, 2
	s_and_b32 s3, s3, 7
	s_lshl_b32 s3, s3, 7
	s_add_u32 s4, s26, 0xfb00
	s_addc_u32 s5, s27, 0
	v_mov_b32_e32 v0, s3
	v_mov_b32_e32 v1, 1
	global_atomic_add v0, v1, s[4:5]
	v_mov_b32_e32 v0, 0
	s_mov_b32 s3, 0
	s_waitcnt vmcnt(0)
.Lb4_spin:
	global_load_dword v1, v0, s[4:5] sc1
	global_load_dword v2, v0, s[4:5] offset:128 sc1
	global_load_dword v3, v0, s[4:5] offset:256 sc1
	global_load_dword v4, v0, s[4:5] offset:384 sc1
	global_load_dword v5, v0, s[4:5] offset:512 sc1
	global_load_dword v6, v0, s[4:5] offset:640 sc1
	global_load_dword v7, v0, s[4:5] offset:768 sc1
	global_load_dword v8, v0, s[4:5] offset:896 sc1
	s_waitcnt vmcnt(0)
	v_add3_u32 v1, v1, v2, v3
	v_add3_u32 v4, v4, v5, v6
	v_add3_u32 v1, v1, v7, v8
	v_add_u32_e32 v1, v1, v4
	v_cmp_eq_u32_e32 vcc, 0x100, v1
	s_cbranch_vccnz .Lb4_done
	s_sleep 1
	s_add_i32 s3, s3, 1
	s_cmp_lt_u32 s3, 0x100000
	s_cbranch_scc1 .Lb4_spin

; __device__ __forceinline__ unsigned xb_ld(unsigned* p)              { return __hip_atomic_load(p, __ATOMIC_RELAXED, __HIP_MEMORY_SCOPE_AGENT); }
; __device__ __forceinline__ unsigned xb_add(unsigned* p, unsigned v) { return __hip_atomic_fetch_add(p, v, __ATOMIC_RELAXED, __HIP_MEMORY_SCOPE_AGENT); }
; #define XB_SPIN(cond, bar) do { unsigned _sp = 0; while (cond) { __builtin_amdgcn_s_sleep(1); \
;     if ((++_sp & 255u) == 0u) { if (xb_ld(&(bar)[XB_TMO])) break; if (_sp > XB_SPIN_CAP) { atomicAdd(&(bar)[XB_TMO], 1u); break; } } } } while (0)
; __device__ __forceinline__ void xcd_barrier(const XcdBarrier& b) {
;     asm volatile("s_waitcnt vmcnt(0)" ::: "memory");
;     __syncthreads();
;     if (threadIdx.x == 0) {
;         unsigned* bar = b.bar;
;         __builtin_amdgcn_s_waitcnt(0);
;         unsigned nloc = b.st[0], nx = b.st[1];
;         if (nloc == 0u) { unsigned uni; xcd_barrier_complete(bar, b.x, nloc, nx, uni); b.st[0] = nloc; b.st[1] = nx; b.st[2] = uni; }
;         const unsigned old = xb_add(&bar[XB_XSUB(b.x)], 1u);
;         const unsigned gen = old / nloc;
;         if (old + 1u == (gen + 1u) * nloc) {
;             __builtin_amdgcn_fence(__ATOMIC_RELEASE, "agent");
;             asm volatile("s_waitcnt vmcnt(0)" ::: "memory");
;             const unsigned og = xb_add(&bar[XB_TOP], 1u);
;             const unsigned tg = og / nx;
;             if (og + 1u == (tg + 1u) * nx) xb_add(&bar[XB_TOPGEN], 1u);
;             else XB_SPIN(xb_ld(&bar[XB_TOPGEN]) == tg, bar);
;             __builtin_amdgcn_fence(__ATOMIC_ACQUIRE, "agent");
;             xb_add(&bar[XB_XGEN(b.x)], 1u);
;             asm volatile("s_waitcnt vmcnt(0)" ::: "memory");
;         } else {
;             XB_SPIN(xb_ld(&bar[XB_XGEN(b.x)]) == gen, bar);
;             __builtin_amdgcn_fence(__ATOMIC_ACQUIRE, "agent");
;             asm volatile("s_waitcnt vmcnt(0)" ::: "memory");
;         }
;     }
;     __syncthreads();
; }
.Lb4_join:
	s_or_b64 exec, exec, s[20:21]
	s_waitcnt lgkmcnt(0)
	s_barrier
	s_branch .LBB0_891
	s_waitcnt vmcnt(0)
	s_barrier
	s_mov_b64 s[20:21], exec
	v_readlane_b32 s4, v246, 3
	v_readlane_b32 s5, v246, 4
	s_and_b64 s[4:5], s[20:21], s[4:5]
	s_mov_b64 exec, s[4:5]
	s_cbranch_execz .LBB0_890
	s_add_i32 s3, 0, 0x23fc0
	v_mov_b32_e32 v0, s3
	s_waitcnt vmcnt(0) expcnt(0) lgkmcnt(0)
	ds_read_b32 v2, v0
	s_add_i32 s3, 0, 0x23fc4
	v_mov_b32_e32 v0, s3
	ds_read_b32 v0, v0
	s_waitcnt lgkmcnt(1)
	v_cmp_ne_u32_e32 vcc, 0, v2
	s_cbranch_vccnz .LBB0_854
	s_add_u32 s4, s26, 0xc200
	s_addc_u32 s5, s27, 0
	s_add_u32 s6, s26, 0xc400
	s_addc_u32 s7, s27, 0
	s_add_u32 s8, s26, 0xc500
	s_addc_u32 s9, s27, 0
	s_add_u32 s10, s26, 0xc600
	s_addc_u32 s11, s27, 0
	s_add_u32 s12, s26, 0xc700
	s_addc_u32 s13, s27, 0
	s_add_u32 s14, s26, 0xc800
	s_addc_u32 s15, s27, 0
	s_add_u32 s16, s26, 0xc900
	s_addc_u32 s17, s27, 0
	s_add_u32 s18, s26, 0xca00
	s_addc_u32 s19, s27, 0
	s_add_u32 s30, s26, 0xcb00
	s_addc_u32 s31, s27, 0
	s_add_u32 s34, s26, 0xcc00
	s_addc_u32 s35, s27, 0
	s_add_u32 s36, s26, 0xcd00
	s_addc_u32 s37, s27, 0
	s_add_u32 s38, s26, 0xce00
	s_addc_u32 s39, s27, 0
	s_add_u32 s40, s26, 0xcf00
	s_addc_u32 s41, s27, 0
	s_add_u32 s42, s26, 0xd000
	s_load_dword s3, s[0:1], 0xc0
	s_addc_u32 s43, s27, 0
	s_add_u32 s44, s26, 0xd100
	s_addc_u32 s45, s27, 0
	s_add_u32 s46, s26, 0xd200
	s_addc_u32 s47, s27, 0
	s_waitcnt lgkmcnt(0)
	s_mul_i32 s3, s23, s3
	s_add_u32 s48, s26, 0xd300
	s_mul_i32 s3, s3, s22
	s_addc_u32 s49, s27, 0
	s_mov_b32 s23, 1
	v_mov_b32_e32 v16, 0
	s_branch .LBB0_843
